# phase-6 epilogue stores now full 128-B lines: 8 rows x 128 B per dwordx4 instruction (permlane16 swap + DPP half-row exchange)
# speedup vs baseline: 1.0198x; 1.0028x over previous
; DI int BIDX() { int b = blockIdx.x; asm volatile("" : "+s"(b)); return b; }
; DI int tile_groups(int MT, int NT) { return (MT >> 6) * ((NT + 7) >> 3) * 512; }
; DI void load_rstd(float (&rs)[4], const float* ssq, int row0, int lr) {
; #pragma unroll
;   for (int mt = 0; mt < 4; ++mt) {
;     const float4* q = (const float4*)(ssq + (size_t)(row0 + mt * 16 + lr) * 16);
;     const float4 a = q[0], b = q[1], c = q[2], d = q[3];
;     const float s = ((a.x + a.y) + (a.z + a.w)) + ((b.x + b.y) + (b.z + b.w)) + ((c.x + c.y) + (c.z + c.w)) + ((d.x + d.y) + (d.z + d.w));
;     rs[mt] = rsqrtf(s * (1.0f / 1024.0f) + EPS);
;   }
; }
; template <int VAR> DI void phase_up(const Params& P, int l, char* smem) {
;     ...
;   for (int vb = BIDX(); vb < tile_groups(128, 32); vb += gridDim.x) {
;     int tm, tn; if (!tile_of(vb, 128, 32, tm, tn)) continue;
;     const int m0 = tm * 128, n0 = tn * 128;
;     const int row0 = m0 + wm * 64, col0 = n0 + wn * 64;
;     f32x4 acc[4][4]; zero_acc(acc);
;     float rs[4]; load_rstd(rs, ssq, row0, lr);
.LBB0_1313:
	s_ashr_i32 s4, s2, 9
	s_lshr_b32 s1, s4, 30
	s_add_i32 s1, s4, s1
	s_ashr_i32 s5, s1, 2
	s_lshl_b32 s1, s5, 6
	s_and_b32 s6, s12, 56
	s_lshl_b32 s5, s5, 5
	s_lshl_b32 s4, s4, 3
	s_or_b32 s1, s1, s6
	s_bfe_u32 s6, s2, 0x30003
	s_sub_i32 s4, s4, s5
	s_bfe_u32 s5, s2, 0x30006
	s_or_b32 s1, s1, s6
	s_or_b32 s4, s4, s5
	s_cmpk_lt_i32 s1, 0x80
	s_cselect_b64 s[6:7], -1, 0
	s_cmp_lt_i32 s4, 32
	s_cselect_b64 s[8:9], -1, 0
	s_and_b64 s[6:7], s[6:7], s[8:9]
	s_andn2_b64 vcc, exec, s[6:7]
	s_cbranch_vccnz .LBB0_1312
	s_lshl_b32 s8, s1, 7
	v_add_u32_e32 v102, s8, v125
	v_ashrrev_i32_e32 v103, 31, v102
	v_readlane_b32 s14, v254, 41
	v_lshlrev_b64 v[0:1], 6, v[102:103]
	v_readlane_b32 s15, v254, 42
	v_or_b32_e32 v98, 16, v102
	v_ashrrev_i32_e32 v99, 31, v98
	v_lshl_add_u64 v[12:13], s[14:15], 0, v[0:1]
	global_load_dwordx4 v[0:3], v[12:13], off offset:32
	global_load_dwordx4 v[4:7], v[12:13], off offset:16
	global_load_dwordx4 v[8:11], v[12:13], off
	s_nop 0
	global_load_dwordx4 v[12:15], v[12:13], off offset:48
	s_lshl_b32 s6, s4, 7
	s_mov_b32 s4, 0x358637bd
	s_mov_b32 s16, 0x3a800000
	s_mov_b32 s1, 0x800000
	v_or_b32_e32 v106, 32, v102
	v_ashrrev_i32_e32 v107, 31, v106
	v_or_b32_e32 v104, 48, v102
	v_ashrrev_i32_e32 v105, 31, v104
	s_ashr_i32 s9, s8, 31
	s_waitcnt vmcnt(7)
	v_mov_b32_e32 v72, v148
	v_or_b32_e32 v100, s6, v124
	s_waitcnt vmcnt(2)
	v_mov_b32_e32 v18, v5
	s_waitcnt vmcnt(1)
	v_mov_b32_e32 v16, v9
	v_mov_b32_e32 v17, v10
	v_mov_b32_e32 v19, v6
	v_mov_b32_e32 v9, v11
	v_mov_b32_e32 v5, v7
	v_mov_b32_e32 v6, v1
	v_pk_add_f32 v[8:9], v[16:17], v[8:9]
	v_pk_add_f32 v[4:5], v[18:19], v[4:5]
	v_pk_add_f32 v[0:1], v[0:1], v[6:7]
	v_mov_b32_e32 v6, v3
	v_pk_add_f32 v[8:9], v[8:9], v[8:9] op_sel:[0,1] op_sel_hi:[1,0]
	v_pk_add_f32 v[4:5], v[4:5], v[4:5] op_sel:[0,1] op_sel_hi:[1,0]
	v_pk_add_f32 v[2:3], v[2:3], v[6:7]
	s_waitcnt vmcnt(0)
	v_mov_b32_e32 v9, v12
	v_mov_b32_e32 v5, v13
	v_mov_b32_e32 v1, v14
	v_mov_b32_e32 v3, v15
	v_pk_add_f32 v[4:5], v[8:9], v[4:5]
	v_pk_add_f32 v[0:1], v[0:1], v[2:3]
	s_nop 0
	v_pk_add_f32 v[16:17], v[4:5], v[0:1]
	v_lshlrev_b64 v[0:1], 6, v[98:99]
	v_lshl_add_u64 v[12:13], s[14:15], 0, v[0:1]
	global_load_dwordx4 v[0:3], v[12:13], off offset:32
	global_load_dwordx4 v[4:7], v[12:13], off offset:16
	global_load_dwordx4 v[8:11], v[12:13], off
	s_nop 0
	global_load_dwordx4 v[12:15], v[12:13], off offset:48
	s_waitcnt vmcnt(2)
	v_mov_b32_e32 v20, v5
	s_waitcnt vmcnt(1)
	v_mov_b32_e32 v18, v9
	v_mov_b32_e32 v19, v10
	v_mov_b32_e32 v21, v6
	v_mov_b32_e32 v9, v11
	v_mov_b32_e32 v5, v7
	v_mov_b32_e32 v6, v1
	v_pk_add_f32 v[8:9], v[18:19], v[8:9]
	v_pk_add_f32 v[4:5], v[20:21], v[4:5]
	v_pk_add_f32 v[0:1], v[0:1], v[6:7]
	v_mov_b32_e32 v6, v3
	v_pk_add_f32 v[8:9], v[8:9], v[8:9] op_sel:[0,1] op_sel_hi:[1,0]
	v_pk_add_f32 v[4:5], v[4:5], v[4:5] op_sel:[0,1] op_sel_hi:[1,0]
	v_pk_add_f32 v[2:3], v[2:3], v[6:7]
	s_waitcnt vmcnt(0)
	v_mov_b32_e32 v9, v12
	v_mov_b32_e32 v5, v13
	v_mov_b32_e32 v1, v14
	v_mov_b32_e32 v3, v15
	v_pk_add_f32 v[4:5], v[8:9], v[4:5]
	v_pk_add_f32 v[0:1], v[0:1], v[2:3]
	v_mov_b32_e32 v3, v16
	v_pk_add_f32 v[0:1], v[4:5], v[0:1]
	s_nop 0
	v_mov_b32_e32 v2, v0
	v_mov_b32_e32 v16, v1
	v_pk_add_f32 v[2:3], v[2:3], v[16:17]
	v_mov_b64_e32 v[0:1], s[4:5]
	v_pk_fma_f32 v[2:3], v[2:3], s[16:17], v[0:1] op_sel_hi:[1,0,0]
	s_nop 0
	v_mul_f32_e32 v4, 0x4b800000, v3
	v_cmp_gt_f32_e64 s[4:5], s1, v3
	v_cmp_gt_f32_e32 vcc, s1, v2
	s_nop 0
	v_cndmask_b32_e64 v3, v3, v4, s[4:5]
	v_rsq_f32_e32 v3, v3
	s_nop 0
	v_mul_f32_e32 v4, 0x45800000, v3
	v_cndmask_b32_e64 v128, v3, v4, s[4:5]
	v_mul_f32_e32 v3, 0x4b800000, v2
	v_cndmask_b32_e32 v2, v2, v3, vcc
	v_rsq_f32_e32 v2, v2
	s_nop 0
	v_mul_f32_e32 v3, 0x45800000, v2
	v_cndmask_b32_e32 v126, v2, v3, vcc
	v_lshlrev_b64 v[2:3], 6, v[106:107]
	v_lshl_add_u64 v[14:15], s[14:15], 0, v[2:3]
	global_load_dwordx4 v[2:5], v[14:15], off offset:32
	global_load_dwordx4 v[6:9], v[14:15], off offset:16
	global_load_dwordx4 v[10:13], v[14:15], off
	s_nop 0
	global_load_dwordx4 v[14:17], v[14:15], off offset:48
	s_waitcnt vmcnt(2)
	v_mov_b32_e32 v20, v7
	s_waitcnt vmcnt(1)
	v_mov_b32_e32 v18, v11
	v_mov_b32_e32 v19, v12
	v_mov_b32_e32 v21, v8
	v_mov_b32_e32 v11, v13
	v_mov_b32_e32 v7, v9
	v_mov_b32_e32 v8, v3
	v_pk_add_f32 v[10:11], v[18:19], v[10:11]
	v_pk_add_f32 v[6:7], v[20:21], v[6:7]
	v_pk_add_f32 v[2:3], v[2:3], v[8:9]
	v_mov_b32_e32 v8, v5
	v_pk_add_f32 v[10:11], v[10:11], v[10:11] op_sel:[0,1] op_sel_hi:[1,0]
	v_pk_add_f32 v[6:7], v[6:7], v[6:7] op_sel:[0,1] op_sel_hi:[1,0]
	v_pk_add_f32 v[4:5], v[4:5], v[8:9]
	s_waitcnt vmcnt(0)
	v_mov_b32_e32 v11, v14
	v_mov_b32_e32 v7, v15
	v_mov_b32_e32 v3, v16
	v_mov_b32_e32 v5, v17
	v_pk_add_f32 v[6:7], v[10:11], v[6:7]
	v_pk_add_f32 v[2:3], v[2:3], v[4:5]
	s_nop 0
	v_pk_add_f32 v[18:19], v[6:7], v[2:3]
	v_lshlrev_b64 v[2:3], 6, v[104:105]
	v_lshl_add_u64 v[14:15], s[14:15], 0, v[2:3]
	global_load_dwordx4 v[2:5], v[14:15], off offset:32
	global_load_dwordx4 v[6:9], v[14:15], off offset:16
	global_load_dwordx4 v[10:13], v[14:15], off
	s_nop 0
	global_load_dwordx4 v[14:17], v[14:15], off offset:48
	s_waitcnt vmcnt(2)
	v_mov_b32_e32 v22, v7
	s_waitcnt vmcnt(1)
	v_mov_b32_e32 v20, v11
	v_mov_b32_e32 v21, v12
	v_mov_b32_e32 v23, v8
	v_mov_b32_e32 v11, v13
	v_mov_b32_e32 v7, v9
	v_mov_b32_e32 v8, v3
	v_pk_add_f32 v[10:11], v[20:21], v[10:11]
	v_pk_add_f32 v[6:7], v[22:23], v[6:7]
	v_pk_add_f32 v[2:3], v[2:3], v[8:9]
	v_mov_b32_e32 v8, v5
	v_pk_add_f32 v[10:11], v[10:11], v[10:11] op_sel:[0,1] op_sel_hi:[1,0]
	v_pk_add_f32 v[6:7], v[6:7], v[6:7] op_sel:[0,1] op_sel_hi:[1,0]
	v_pk_add_f32 v[4:5], v[4:5], v[8:9]
	s_waitcnt vmcnt(0)
; DI int TIDX() { int t = threadIdx.x; asm volatile("" : "+v"(t)); return t; }
; #define GL_LOAD(s_, kt_) if (VAR != 1) { a##s_##0 = GL_A(0, kt_); a##s_##1 = GL_A(1, kt_); a##s_##2 = GL_A(2, kt_); a##s_##3 = GL_A(3, kt_); b##s_##0 = GL_B(0, kt_); b##s_##1 = GL_B(1, kt_); b##s_##2 = GL_B(2, kt_); b##s_##3 = GL_B(3, kt_); }
; #define LDS_STORE(s_, buf_) if (VAR != 2) { LDS_ST1(sA, 0, buf_, a##s_##0) LDS_ST1(sA, 1, buf_, a##s_##1) LDS_ST1(sA, 2, buf_, a##s_##2) LDS_ST1(sA, 3, buf_, a##s_##3) LDS_ST1(sB, 0, buf_, b##s_##0) LDS_ST1(sB, 1, buf_, b##s_##1) LDS_ST1(sB, 2, buf_, b##s_##2) LDS_ST1(sB, 3, buf_, b##s_##3) }
;   const int tid = TIDX(), lane = tid & 63, wid = tid >> 6, wm = wid >> 1, wn = wid & 1, lr = lane & 15, g = lane >> 4;
;   char* sA = smem; char* sB = smem + 2 * LTILE;
;   uint4 a00 = {}, a01 = {}, a02 = {}, a03 = {}, b00 = {}, b01 = {}, b02 = {}, b03 = {}, a10 = {}, a11 = {}, a12 = {}, a13 = {}, b10 = {}, b11 = {}, b12 = {}, b13 = {};
;   constexpr int nk = NK;
;   const int sw0 = (g ^ ((lr >> 1) & 7)) << 4, sw1 = sw0 ^ 64;
;   const int r0 = tid >> 3, kc = tid & 7, kcs = kc ^ ((r0 >> 1) & 7);
;     ...
;   GL_LOAD(0, 0)
;   GL_LOAD(1, 1)
;   LDS_STORE(0, 0)
;   if (VAR != 4) __syncthreads();
	v_mov_b32_e32 v11, v14
	v_mov_b32_e32 v7, v15
	v_mov_b32_e32 v3, v16
	v_mov_b32_e32 v5, v17
	v_pk_add_f32 v[6:7], v[10:11], v[6:7]
	v_pk_add_f32 v[2:3], v[2:3], v[4:5]
	v_mov_b32_e32 v5, v18
	v_pk_add_f32 v[2:3], v[6:7], v[2:3]
	v_ashrrev_i32_e32 v64, 3, v72
	v_mov_b32_e32 v4, v2
	v_mov_b32_e32 v18, v3
	v_pk_add_f32 v[2:3], v[4:5], v[18:19]
	v_ashrrev_i32_e32 v65, 31, v64
	v_pk_fma_f32 v[0:1], v[2:3], s[16:17], v[0:1] op_sel_hi:[1,0,0]
	v_and_b32_e32 v75, 48, v72
	v_mul_f32_e32 v2, 0x4b800000, v1
	v_cmp_gt_f32_e64 s[4:5], s1, v1
	v_cmp_gt_f32_e32 vcc, s1, v0
	v_lshlrev_b64 v[16:17], 11, v[64:65]
	v_cndmask_b32_e64 v1, v1, v2, s[4:5]
	v_rsq_f32_e32 v1, v1
	v_lshlrev_b32_e32 v65, 4, v72
	v_and_b32_e32 v150, 0x70, v65
	v_add_u32_e32 v66, 32, v64
	v_mul_f32_e32 v2, 0x45800000, v1
	v_cndmask_b32_e64 v129, v1, v2, s[4:5]
	v_mul_f32_e32 v1, 0x4b800000, v0
	v_cndmask_b32_e32 v0, v0, v1, vcc
	v_rsq_f32_e32 v0, v0
	s_lshl_b64 s[4:5], s[8:9], 11
	v_readlane_b32 s8, v254, 43
	v_readlane_b32 s9, v254, 44
	v_mul_f32_e32 v1, 0x45800000, v0
	s_add_u32 s4, s8, s4
	v_cndmask_b32_e32 v127, v0, v1, vcc
	s_addc_u32 s5, s9, s5
	v_lshlrev_b32_e32 v0, 3, v72
	s_ashr_i32 s7, s6, 31
	v_and_b32_e32 v74, 0x70, v0
	v_bitop3_b32 v134, v0, v75, s23 bitop3:0x6c
	v_lshl_add_u64 v[0:1], s[4:5], 0, v[16:17]
	v_add_u32_e32 v68, 64, v64
	v_add_u32_e32 v70, 0x60, v64
	s_lshl_b64 s[6:7], s[6:7], 11
	v_lshl_add_u64 v[108:109], v[0:1], 0, v[150:151]
	v_ashrrev_i32_e32 v67, 31, v66
	v_ashrrev_i32_e32 v69, 31, v68
	v_ashrrev_i32_e32 v71, 31, v70
	s_add_u32 s6, s10, s6
	v_lshlrev_b64 v[20:21], 11, v[66:67]
	v_lshlrev_b64 v[24:25], 11, v[68:69]
	v_lshlrev_b64 v[28:29], 11, v[70:71]
	s_addc_u32 s7, s11, s7
	v_lshl_add_u64 v[4:5], s[4:5], 0, v[20:21]
	v_lshl_add_u64 v[8:9], s[4:5], 0, v[24:25]
	v_lshl_add_u64 v[12:13], s[4:5], 0, v[28:29]
	v_lshl_add_u64 v[110:111], v[4:5], 0, v[150:151]
	v_lshl_add_u64 v[112:113], v[8:9], 0, v[150:151]
	v_lshl_add_u64 v[114:115], v[12:13], 0, v[150:151]
	v_lshl_add_u64 v[16:17], s[6:7], 0, v[16:17]
	v_lshl_add_u64 v[116:117], v[16:17], 0, v[150:151]
	v_lshl_add_u64 v[20:21], s[6:7], 0, v[20:21]
	v_lshl_add_u64 v[118:119], v[20:21], 0, v[150:151]
	v_lshl_add_u64 v[24:25], s[6:7], 0, v[24:25]
	v_lshl_add_u64 v[120:121], v[24:25], 0, v[150:151]
	v_lshl_add_u64 v[28:29], s[6:7], 0, v[28:29]
	v_lshl_add_u64 v[122:123], v[28:29], 0, v[150:151]
	v_bitop3_b32 v65, v65, s23, v72 bitop3:0x48
	v_lshl_or_b32 v101, v64, 7, v65
	v_and_b32_e32 v73, 15, v72
	v_lshl_or_b32 v131, v66, 7, v65
	v_lshl_or_b32 v132, v68, 7, v65
	v_lshl_or_b32 v130, v70, 7, v65
	v_xor_b32_e32 v135, 64, v134
	v_writelane_b32 v255, s60, 0
	v_writelane_b32 v255, s61, 1
	v_writelane_b32 v255, s62, 2
	v_writelane_b32 v255, s63, 3
	v_writelane_b32 v255, s64, 4
	v_writelane_b32 v255, s65, 5
	v_writelane_b32 v255, s66, 6
	v_writelane_b32 v255, s67, 7
	v_writelane_b32 v255, s68, 8
	v_writelane_b32 v255, s69, 9
	v_writelane_b32 v255, s70, 10
	v_writelane_b32 v255, s71, 11
	v_writelane_b32 v255, s72, 12
	v_writelane_b32 v255, s73, 13
	v_writelane_b32 v255, s74, 14
	v_writelane_b32 v255, s75, 15
	v_mov_b32_e32 v3, v101
	v_and_b32_e32 v3, 0xffffff80, v3
	s_nop 0
	v_readfirstlane_b32 s60, v3
	v_add_u32_e32 v3, 0x4000, v101
	v_and_b32_e32 v3, 0xffffff80, v3
	s_nop 0
	v_readfirstlane_b32 s61, v3
	v_add_u32_e32 v3, 0x8000, v101
	v_and_b32_e32 v3, 0xffffff80, v3
	s_nop 0
	v_readfirstlane_b32 s62, v3
	v_add_u32_e32 v3, 0xc000, v101
	v_and_b32_e32 v3, 0xffffff80, v3
	s_nop 0
	v_readfirstlane_b32 s63, v3
	v_mov_b32_e32 v3, v130
	v_and_b32_e32 v3, 0xffffff80, v3
	s_nop 0
	v_readfirstlane_b32 s64, v3
	v_add_u32_e32 v3, 0x4000, v130
	v_and_b32_e32 v3, 0xffffff80, v3
	s_nop 0
	v_readfirstlane_b32 s65, v3
	v_add_u32_e32 v3, 0x8000, v130
	v_and_b32_e32 v3, 0xffffff80, v3
	s_nop 0
	v_readfirstlane_b32 s66, v3
	v_add_u32_e32 v3, 0xc000, v130
	v_and_b32_e32 v3, 0xffffff80, v3
	s_nop 0
	v_readfirstlane_b32 s67, v3
	v_mov_b32_e32 v3, v131
	v_and_b32_e32 v3, 0xffffff80, v3
	s_nop 0
	v_readfirstlane_b32 s68, v3
	v_add_u32_e32 v3, 0x4000, v131
	v_and_b32_e32 v3, 0xffffff80, v3
	s_nop 0
	v_readfirstlane_b32 s69, v3
	v_add_u32_e32 v3, 0x8000, v131
	v_and_b32_e32 v3, 0xffffff80, v3
	s_nop 0
	v_readfirstlane_b32 s70, v3
	v_add_u32_e32 v3, 0xc000, v131
	v_and_b32_e32 v3, 0xffffff80, v3
	s_nop 0
	v_readfirstlane_b32 s71, v3
	v_mov_b32_e32 v3, v132
	v_and_b32_e32 v3, 0xffffff80, v3
	s_nop 0
	v_readfirstlane_b32 s72, v3
	v_add_u32_e32 v3, 0x4000, v132
	v_and_b32_e32 v3, 0xffffff80, v3
	s_nop 0
	v_readfirstlane_b32 s73, v3
	v_add_u32_e32 v3, 0x8000, v132
	v_and_b32_e32 v3, 0xffffff80, v3
	s_nop 0
	v_readfirstlane_b32 s74, v3
	v_add_u32_e32 v3, 0xc000, v132
	v_and_b32_e32 v3, 0xffffff80, v3
	s_nop 0
	v_readfirstlane_b32 s75, v3
	v_and_b32_e32 v30, 7, v148
	v_bfe_u32 v31, v148, 4, 3
	v_xor_b32_e32 v31, v31, v30
	v_sub_u32_e32 v31, v31, v30
	v_lshlrev_b32_e32 v30, 4, v31
	v_ashrrev_i32_e32 v31, 31, v30
	v_lshl_add_u64 v[0:1], v[108:109], 0, v[30:31]
	s_mov_b32 m0, s60
	s_nop 0
	global_load_lds_dwordx4 v[0:1], off
	v_lshrrev_b32_e32 v0, 1, v72
	v_and_or_b32 v0, v0, s24, v73
	v_lshlrev_b32_e32 v137, 7, v0
	v_lshlrev_b32_e32 v0, 7, v72
	v_and_b32_e32 v146, 0x2780, v0
	v_bitop3_b32 v133, v137, v74, v75 bitop3:0xf6
	v_or_b32_e32 v136, v146, v134
	v_bitop3_b32 v134, v137, v134, 64 bitop3:0xf6
	v_or_b32_e32 v135, v146, v135
	v_lshl_add_u64 v[4:5], v[110:111], 0, v[30:31]
	s_mov_b32 m0, s68
	s_nop 0
	global_load_lds_dwordx4 v[4:5], off
	v_lshl_add_u64 v[8:9], v[112:113], 0, v[30:31]
	s_mov_b32 m0, s72
	s_nop 0
	global_load_lds_dwordx4 v[8:9], off
	v_lshl_add_u64 v[12:13], v[114:115], 0, v[30:31]
	s_mov_b32 m0, s64
	s_nop 0
	global_load_lds_dwordx4 v[12:13], off
	v_lshl_add_u64 v[16:17], v[116:117], 0, v[30:31]
	s_mov_b32 m0, s62
	s_nop 0
	global_load_lds_dwordx4 v[16:17], off
	v_lshl_add_u64 v[20:21], v[118:119], 0, v[30:31]
	s_mov_b32 m0, s70
	s_nop 0
	global_load_lds_dwordx4 v[20:21], off
	v_lshl_add_u64 v[24:25], v[120:121], 0, v[30:31]
	s_mov_b32 m0, s74
	s_nop 0
	global_load_lds_dwordx4 v[24:25], off
	v_lshl_add_u64 v[28:29], v[122:123], 0, v[30:31]
	s_mov_b32 m0, s66
	s_nop 0
	global_load_lds_dwordx4 v[28:29], off
	s_waitcnt lgkmcnt(0)
	s_waitcnt vmcnt(0)
	s_barrier
; #define GL_LOAD(s_, kt_) if (VAR != 1) { a##s_##0 = GL_A(0, kt_); a##s_##1 = GL_A(1, kt_); a##s_##2 = GL_A(2, kt_); a##s_##3 = GL_A(3, kt_); b##s_##0 = GL_B(0, kt_); b##s_##1 = GL_B(1, kt_); b##s_##2 = GL_B(2, kt_); b##s_##3 = GL_B(3, kt_); }
; #define LDS_STORE(s_, buf_) if (VAR != 2) { LDS_ST1(sA, 0, buf_, a##s_##0) LDS_ST1(sA, 1, buf_, a##s_##1) LDS_ST1(sA, 2, buf_, a##s_##2) LDS_ST1(sA, 3, buf_, a##s_##3) LDS_ST1(sB, 0, buf_, b##s_##0) LDS_ST1(sB, 1, buf_, b##s_##1) LDS_ST1(sB, 2, buf_, b##s_##2) LDS_ST1(sB, 3, buf_, b##s_##3) }
;     ...
;   GL_LOAD(0, 0)
;   GL_LOAD(1, 1)
;   LDS_STORE(0, 0)
;   if (VAR != 4) __syncthreads();
; #pragma unroll
;   for (int kt = 0; kt < nk; kt += 2) {
;     if (kt + 2 < nk) { GL_LOAD(0, kt + 2) }
;     MMA_TILE(0)
;     LDS_STORE(1, 1)
;     if (VAR != 4) __syncthreads();
;     if (kt + 3 < nk) { GL_LOAD(1, kt + 3) }
;     MMA_TILE(1)
;     if (kt + 2 < nk) { LDS_STORE(0, 0) }
;     if (VAR != 4) __syncthreads();
	s_setprio 1
	ds_read_b128 v[64:67], v133
	ds_read_b128 v[68:71], v136 offset:32768
	s_waitcnt lgkmcnt(0)
	v_mfma_f32_16x16x32_f16 v[138:141], v[68:71], v[64:67], 0
	ds_read_b128 v[72:75], v133 offset:2048
	ds_read_b128 v[76:79], v136 offset:34816
	s_waitcnt lgkmcnt(1)
	v_mfma_f32_16x16x32_f16 v[158:161], v[68:71], v[72:75], 0
	ds_read_b128 v[80:83], v133 offset:4096
	ds_read_b128 v[84:87], v136 offset:36864
	s_waitcnt lgkmcnt(2)
	v_mfma_f32_16x16x32_f16 v[142:145], v[76:79], v[64:67], 0
	ds_read_b128 v[88:91], v133 offset:6144
	ds_read_b128 v[92:95], v136 offset:38912
	v_mfma_f32_16x16x32_f16 v[162:165], v[76:79], v[72:75], 0
	ds_read_b128 v[202:205], v135 offset:32768
	ds_read_b128 v[206:209], v134 offset:2048
	s_waitcnt lgkmcnt(5)
	v_mfma_f32_16x16x32_f16 v[190:193], v[68:71], v[80:83], 0
	ds_read_b128 v[210:213], v135 offset:34816
	ds_read_b128 v[220:223], v134 offset:4096
	s_waitcnt lgkmcnt(5)
	v_mfma_f32_16x16x32_f16 v[68:71], v[68:71], v[88:91], 0
	ds_read_b128 v[224:227], v135 offset:36864
	v_mfma_f32_16x16x32_f16 v[194:197], v[76:79], v[80:83], 0
	ds_read_b128 v[228:231], v134 offset:6144
	v_mfma_f32_16x16x32_f16 v[76:79], v[76:79], v[88:91], 0
	ds_read_b128 v[232:235], v135 offset:38912
	v_mfma_f32_16x16x32_f16 v[154:157], v[84:87], v[64:67], 0
	v_mfma_f32_16x16x32_f16 v[166:169], v[84:87], v[72:75], 0
	s_waitcnt lgkmcnt(7)
	v_mfma_f32_16x16x32_f16 v[64:67], v[92:95], v[64:67], 0
	v_mfma_f32_16x16x32_f16 v[72:75], v[92:95], v[72:75], 0
	v_mfma_f32_16x16x32_f16 v[198:201], v[84:87], v[80:83], 0
	v_and_b32_e32 v62, 7, v148
	v_bfe_u32 v63, v148, 4, 3
	v_xor_b32_e32 v63, v63, v62
	v_sub_u32_e32 v63, v63, v62
	v_lshlrev_b32_e32 v62, 4, v63
	v_add_u32_e32 v62, 0x80, v62
	v_ashrrev_i32_e32 v63, 31, v62
	v_mfma_f32_16x16x32_f16 v[84:87], v[84:87], v[88:91], 0
	v_lshl_add_u64 v[32:33], v[108:109], 0, v[62:63]
	s_mov_b32 m0, s61
	s_nop 0
	global_load_lds_dwordx4 v[32:33], off
	v_lshl_add_u64 v[36:37], v[110:111], 0, v[62:63]
	s_mov_b32 m0, s69
	s_nop 0
	global_load_lds_dwordx4 v[36:37], off
	v_mfma_f32_16x16x32_f16 v[80:83], v[92:95], v[80:83], 0
	v_lshl_add_u64 v[40:41], v[112:113], 0, v[62:63]
	s_mov_b32 m0, s73
	s_nop 0
	global_load_lds_dwordx4 v[40:41], off
	v_lshl_add_u64 v[44:45], v[114:115], 0, v[62:63]
	s_mov_b32 m0, s65
	s_nop 0
	global_load_lds_dwordx4 v[44:45], off
	v_mfma_f32_16x16x32_f16 v[88:91], v[92:95], v[88:91], 0
	ds_read_b128 v[92:95], v134
	v_lshl_add_u64 v[48:49], v[116:117], 0, v[62:63]
	s_mov_b32 m0, s63
	s_nop 0
	global_load_lds_dwordx4 v[48:49], off
	v_lshl_add_u64 v[52:53], v[118:119], 0, v[62:63]
	s_mov_b32 m0, s71
	s_nop 0
	global_load_lds_dwordx4 v[52:53], off
	v_lshl_add_u64 v[56:57], v[120:121], 0, v[62:63]
	s_mov_b32 m0, s75
	s_nop 0
	global_load_lds_dwordx4 v[56:57], off
	v_lshl_add_u64 v[60:61], v[122:123], 0, v[62:63]
	s_mov_b32 m0, s67
	s_nop 0
	global_load_lds_dwordx4 v[60:61], off
	s_waitcnt vmcnt(0) lgkmcnt(0)
	s_barrier
	v_mfma_f32_16x16x32_f16 v[138:141], v[202:205], v[92:95], v[138:141]
	v_mfma_f32_16x16x32_f16 v[142:145], v[210:213], v[92:95], v[142:145]
	v_mfma_f32_16x16x32_f16 v[154:157], v[224:227], v[92:95], v[154:157]
	v_mfma_f32_16x16x32_f16 v[64:67], v[232:235], v[92:95], v[64:67]
	v_mfma_f32_16x16x32_f16 v[92:95], v[202:205], v[206:209], v[158:161]
	v_mfma_f32_16x16x32_f16 v[158:161], v[210:213], v[206:209], v[162:165]
	v_mfma_f32_16x16x32_f16 v[162:165], v[224:227], v[206:209], v[166:169]
	v_mfma_f32_16x16x32_f16 v[166:169], v[202:205], v[220:223], v[190:193]
	v_mfma_f32_16x16x32_f16 v[68:71], v[202:205], v[228:231], v[68:71]
	ds_read_b128 v[202:205], v136 offset:49152
	v_mfma_f32_16x16x32_f16 v[190:193], v[210:213], v[220:223], v[194:197]
	v_mfma_f32_16x16x32_f16 v[76:79], v[210:213], v[228:231], v[76:79]
	ds_read_b128 v[210:213], v136 offset:51200
	v_and_b32_e32 v30, 7, v148
	v_bfe_u32 v31, v148, 4, 3
	v_xor_b32_e32 v31, v31, v30
	v_sub_u32_e32 v31, v31, v30
	v_lshlrev_b32_e32 v30, 4, v31
	v_add_u32_e32 v30, 0x100, v30
	v_ashrrev_i32_e32 v31, 31, v30
	v_mfma_f32_16x16x32_f16 v[72:75], v[232:235], v[206:209], v[72:75]
	ds_read_b128 v[206:209], v133 offset:18432
	v_mfma_f32_16x16x32_f16 v[194:197], v[224:227], v[220:223], v[198:201]
	s_nop 2
	ds_read_b128 v[198:201], v133 offset:16384
	v_mfma_f32_16x16x32_f16 v[84:87], v[224:227], v[228:231], v[84:87]
	ds_read_b128 v[224:227], v136 offset:53248
	v_mfma_f32_16x16x32_f16 v[80:83], v[232:235], v[220:223], v[80:83]
	ds_read_b128 v[220:223], v133 offset:20480
	v_mfma_f32_16x16x32_f16 v[88:91], v[232:235], v[228:231], v[88:91]
	ds_read_b128 v[228:231], v133 offset:22528
	s_waitcnt lgkmcnt(3)
	v_mfma_f32_16x16x32_f16 v[138:141], v[202:205], v[198:201], v[138:141]
	ds_read_b128 v[232:235], v136 offset:55296
	v_mfma_f32_16x16x32_f16 v[92:95], v[202:205], v[206:209], v[92:95]
	v_lshl_add_u64 v[0:1], v[108:109], 0, v[30:31]
	s_mov_b32 m0, s60
	s_nop 0
	global_load_lds_dwordx4 v[0:1], off
	v_mfma_f32_16x16x32_f16 v[142:145], v[210:213], v[198:201], v[142:145]
	v_lshl_add_u64 v[4:5], v[110:111], 0, v[30:31]
	s_mov_b32 m0, s68
	s_nop 0
	global_load_lds_dwordx4 v[4:5], off
	v_mfma_f32_16x16x32_f16 v[158:161], v[210:213], v[206:209], v[158:161]
	v_lshl_add_u64 v[8:9], v[112:113], 0, v[30:31]
	s_mov_b32 m0, s72
	s_nop 0
	global_load_lds_dwordx4 v[8:9], off
	s_waitcnt lgkmcnt(2)
	v_mfma_f32_16x16x32_f16 v[166:169], v[202:205], v[220:223], v[166:169]
	v_lshl_add_u64 v[12:13], v[114:115], 0, v[30:31]
	s_mov_b32 m0, s64
	s_nop 0
	global_load_lds_dwordx4 v[12:13], off
	s_waitcnt lgkmcnt(1)
; #define GL_LOAD(s_, kt_) if (VAR != 1) { a##s_##0 = GL_A(0, kt_); a##s_##1 = GL_A(1, kt_); a##s_##2 = GL_A(2, kt_); a##s_##3 = GL_A(3, kt_); b##s_##0 = GL_B(0, kt_); b##s_##1 = GL_B(1, kt_); b##s_##2 = GL_B(2, kt_); b##s_##3 = GL_B(3, kt_); }
; #define LDS_STORE(s_, buf_) if (VAR != 2) { LDS_ST1(sA, 0, buf_, a##s_##0) LDS_ST1(sA, 1, buf_, a##s_##1) LDS_ST1(sA, 2, buf_, a##s_##2) LDS_ST1(sA, 3, buf_, a##s_##3) LDS_ST1(sB, 0, buf_, b##s_##0) LDS_ST1(sB, 1, buf_, b##s_##1) LDS_ST1(sB, 2, buf_, b##s_##2) LDS_ST1(sB, 3, buf_, b##s_##3) }
;     ...
;   GL_LOAD(0, 0)
;   GL_LOAD(1, 1)
;   LDS_STORE(0, 0)
;   if (VAR != 4) __syncthreads();
; #pragma unroll
;   for (int kt = 0; kt < nk; kt += 2) {
;     if (kt + 2 < nk) { GL_LOAD(0, kt + 2) }
;     MMA_TILE(0)
;     LDS_STORE(1, 1)
;     if (VAR != 4) __syncthreads();
;     if (kt + 3 < nk) { GL_LOAD(1, kt + 3) }
;     MMA_TILE(1)
;     if (kt + 2 < nk) { LDS_STORE(0, 0) }
;     if (VAR != 4) __syncthreads();
	v_mfma_f32_16x16x32_f16 v[68:71], v[202:205], v[228:231], v[68:71]
	ds_read_b128 v[202:205], v135 offset:49152
	v_mfma_f32_16x16x32_f16 v[190:193], v[210:213], v[220:223], v[190:193]
	v_lshl_add_u64 v[16:17], v[116:117], 0, v[30:31]
	s_mov_b32 m0, s62
	s_nop 0
	global_load_lds_dwordx4 v[16:17], off
	v_mfma_f32_16x16x32_f16 v[76:79], v[210:213], v[228:231], v[76:79]
	ds_read_b128 v[210:213], v135 offset:51200
	v_mfma_f32_16x16x32_f16 v[154:157], v[224:227], v[198:201], v[154:157]
	v_lshl_add_u64 v[20:21], v[118:119], 0, v[30:31]
	s_mov_b32 m0, s70
	s_nop 0
	global_load_lds_dwordx4 v[20:21], off
	v_mfma_f32_16x16x32_f16 v[162:165], v[224:227], v[206:209], v[162:165]
	v_lshl_add_u64 v[24:25], v[120:121], 0, v[30:31]
	s_mov_b32 m0, s74
	s_nop 0
	global_load_lds_dwordx4 v[24:25], off
	s_waitcnt lgkmcnt(2)
	v_mfma_f32_16x16x32_f16 v[64:67], v[232:235], v[198:201], v[64:67]
	ds_read_b128 v[198:201], v134 offset:16384
	v_mfma_f32_16x16x32_f16 v[72:75], v[232:235], v[206:209], v[72:75]
	ds_read_b128 v[206:209], v134 offset:18432
	v_mfma_f32_16x16x32_f16 v[194:197], v[224:227], v[220:223], v[194:197]
	v_lshl_add_u64 v[28:29], v[122:123], 0, v[30:31]
	s_mov_b32 m0, s66
	s_nop 0
	global_load_lds_dwordx4 v[28:29], off
	v_mfma_f32_16x16x32_f16 v[84:87], v[224:227], v[228:231], v[84:87]
	ds_read_b128 v[224:227], v135 offset:53248
	v_mfma_f32_16x16x32_f16 v[80:83], v[232:235], v[220:223], v[80:83]
	ds_read_b128 v[220:223], v134 offset:20480
	v_mfma_f32_16x16x32_f16 v[88:91], v[232:235], v[228:231], v[88:91]
	ds_read_b128 v[228:231], v134 offset:22528
	ds_read_b128 v[232:235], v135 offset:55296
	s_waitcnt vmcnt(0) lgkmcnt(0)
	s_barrier
	v_mfma_f32_16x16x32_f16 v[138:141], v[202:205], v[198:201], v[138:141]
	v_mfma_f32_16x16x32_f16 v[92:95], v[202:205], v[206:209], v[92:95]
	v_mfma_f32_16x16x32_f16 v[142:145], v[210:213], v[198:201], v[142:145]
	v_mfma_f32_16x16x32_f16 v[158:161], v[210:213], v[206:209], v[158:161]
	v_mfma_f32_16x16x32_f16 v[166:169], v[202:205], v[220:223], v[166:169]
	v_mfma_f32_16x16x32_f16 v[68:71], v[202:205], v[228:231], v[68:71]
	ds_read_b128 v[202:205], v136 offset:32768
	v_mfma_f32_16x16x32_f16 v[190:193], v[210:213], v[220:223], v[190:193]
	v_mfma_f32_16x16x32_f16 v[76:79], v[210:213], v[228:231], v[76:79]
	ds_read_b128 v[210:213], v136 offset:34816
	v_mfma_f32_16x16x32_f16 v[154:157], v[224:227], v[198:201], v[154:157]
	v_mfma_f32_16x16x32_f16 v[162:165], v[224:227], v[206:209], v[162:165]
	v_mfma_f32_16x16x32_f16 v[64:67], v[232:235], v[198:201], v[64:67]
	ds_read_b128 v[198:201], v133
	v_mfma_f32_16x16x32_f16 v[72:75], v[232:235], v[206:209], v[72:75]
	ds_read_b128 v[206:209], v133 offset:2048
	v_mfma_f32_16x16x32_f16 v[194:197], v[224:227], v[220:223], v[194:197]
	v_and_b32_e32 v62, 7, v148
	v_bfe_u32 v63, v148, 4, 3
	v_xor_b32_e32 v63, v63, v62
	v_sub_u32_e32 v63, v63, v62
	v_lshlrev_b32_e32 v62, 4, v63
	v_add_u32_e32 v62, 0x180, v62
	v_ashrrev_i32_e32 v63, 31, v62
	v_mfma_f32_16x16x32_f16 v[84:87], v[224:227], v[228:231], v[84:87]
	ds_read_b128 v[224:227], v136 offset:36864
	v_mfma_f32_16x16x32_f16 v[80:83], v[232:235], v[220:223], v[80:83]
	ds_read_b128 v[220:223], v133 offset:4096
	v_mfma_f32_16x16x32_f16 v[88:91], v[232:235], v[228:231], v[88:91]
	ds_read_b128 v[228:231], v133 offset:6144
	s_waitcnt lgkmcnt(4)
	v_mfma_f32_16x16x32_f16 v[138:141], v[202:205], v[198:201], v[138:141]
	ds_read_b128 v[232:235], v136 offset:38912
	s_waitcnt lgkmcnt(4)
	v_mfma_f32_16x16x32_f16 v[92:95], v[202:205], v[206:209], v[92:95]
	v_lshl_add_u64 v[32:33], v[108:109], 0, v[62:63]
	s_mov_b32 m0, s61
	s_nop 0
	global_load_lds_dwordx4 v[32:33], off
	v_mfma_f32_16x16x32_f16 v[142:145], v[210:213], v[198:201], v[142:145]
	v_lshl_add_u64 v[36:37], v[110:111], 0, v[62:63]
	s_mov_b32 m0, s69
	s_nop 0
	global_load_lds_dwordx4 v[36:37], off
	v_mfma_f32_16x16x32_f16 v[158:161], v[210:213], v[206:209], v[158:161]
	v_lshl_add_u64 v[40:41], v[112:113], 0, v[62:63]
	s_mov_b32 m0, s73
	s_nop 0
	global_load_lds_dwordx4 v[40:41], off
	s_waitcnt lgkmcnt(2)
	v_mfma_f32_16x16x32_f16 v[166:169], v[202:205], v[220:223], v[166:169]
	v_lshl_add_u64 v[44:45], v[114:115], 0, v[62:63]
	s_mov_b32 m0, s65
	s_nop 0
	global_load_lds_dwordx4 v[44:45], off
	s_waitcnt lgkmcnt(1)
	v_mfma_f32_16x16x32_f16 v[68:71], v[202:205], v[228:231], v[68:71]
	ds_read_b128 v[202:205], v135 offset:32768
	v_mfma_f32_16x16x32_f16 v[190:193], v[210:213], v[220:223], v[190:193]
	v_lshl_add_u64 v[48:49], v[116:117], 0, v[62:63]
	s_mov_b32 m0, s63
	s_nop 0
	global_load_lds_dwordx4 v[48:49], off
	v_mfma_f32_16x16x32_f16 v[76:79], v[210:213], v[228:231], v[76:79]
	ds_read_b128 v[210:213], v135 offset:34816
	v_mfma_f32_16x16x32_f16 v[154:157], v[224:227], v[198:201], v[154:157]
	v_lshl_add_u64 v[52:53], v[118:119], 0, v[62:63]
	s_mov_b32 m0, s71
	s_nop 0
	global_load_lds_dwordx4 v[52:53], off
	v_mfma_f32_16x16x32_f16 v[162:165], v[224:227], v[206:209], v[162:165]
	v_lshl_add_u64 v[56:57], v[120:121], 0, v[62:63]
	s_mov_b32 m0, s75
	s_nop 0
	global_load_lds_dwordx4 v[56:57], off
	s_waitcnt lgkmcnt(2)
	v_mfma_f32_16x16x32_f16 v[64:67], v[232:235], v[198:201], v[64:67]
	ds_read_b128 v[198:201], v134
	v_mfma_f32_16x16x32_f16 v[72:75], v[232:235], v[206:209], v[72:75]
	ds_read_b128 v[206:209], v134 offset:2048
	v_mfma_f32_16x16x32_f16 v[194:197], v[224:227], v[220:223], v[194:197]
	v_lshl_add_u64 v[60:61], v[122:123], 0, v[62:63]
	s_mov_b32 m0, s67
	s_nop 0
	global_load_lds_dwordx4 v[60:61], off
	v_mfma_f32_16x16x32_f16 v[84:87], v[224:227], v[228:231], v[84:87]
	ds_read_b128 v[224:227], v135 offset:36864
	v_mfma_f32_16x16x32_f16 v[80:83], v[232:235], v[220:223], v[80:83]
	ds_read_b128 v[220:223], v134 offset:4096
	v_mfma_f32_16x16x32_f16 v[88:91], v[232:235], v[228:231], v[88:91]
	ds_read_b128 v[228:231], v134 offset:6144
	ds_read_b128 v[232:235], v135 offset:38912
	s_waitcnt vmcnt(0) lgkmcnt(0)
	s_barrier
; #define GL_LOAD(s_, kt_) if (VAR != 1) { a##s_##0 = GL_A(0, kt_); a##s_##1 = GL_A(1, kt_); a##s_##2 = GL_A(2, kt_); a##s_##3 = GL_A(3, kt_); b##s_##0 = GL_B(0, kt_); b##s_##1 = GL_B(1, kt_); b##s_##2 = GL_B(2, kt_); b##s_##3 = GL_B(3, kt_); }
; #define LDS_STORE(s_, buf_) if (VAR != 2) { LDS_ST1(sA, 0, buf_, a##s_##0) LDS_ST1(sA, 1, buf_, a##s_##1) LDS_ST1(sA, 2, buf_, a##s_##2) LDS_ST1(sA, 3, buf_, a##s_##3) LDS_ST1(sB, 0, buf_, b##s_##0) LDS_ST1(sB, 1, buf_, b##s_##1) LDS_ST1(sB, 2, buf_, b##s_##2) LDS_ST1(sB, 3, buf_, b##s_##3) }
;     ...
;   GL_LOAD(0, 0)
;   GL_LOAD(1, 1)
;   LDS_STORE(0, 0)
;   if (VAR != 4) __syncthreads();
; #pragma unroll
;   for (int kt = 0; kt < nk; kt += 2) {
;     if (kt + 2 < nk) { GL_LOAD(0, kt + 2) }
;     MMA_TILE(0)
;     LDS_STORE(1, 1)
;     if (VAR != 4) __syncthreads();
;     if (kt + 3 < nk) { GL_LOAD(1, kt + 3) }
;     MMA_TILE(1)
;     if (kt + 2 < nk) { LDS_STORE(0, 0) }
;     if (VAR != 4) __syncthreads();
	v_mfma_f32_16x16x32_f16 v[138:141], v[202:205], v[198:201], v[138:141]
	v_mfma_f32_16x16x32_f16 v[92:95], v[202:205], v[206:209], v[92:95]
	v_mfma_f32_16x16x32_f16 v[142:145], v[210:213], v[198:201], v[142:145]
	v_mfma_f32_16x16x32_f16 v[158:161], v[210:213], v[206:209], v[158:161]
	v_mfma_f32_16x16x32_f16 v[166:169], v[202:205], v[220:223], v[166:169]
	v_mfma_f32_16x16x32_f16 v[68:71], v[202:205], v[228:231], v[68:71]
	ds_read_b128 v[202:205], v136 offset:49152
	v_mfma_f32_16x16x32_f16 v[190:193], v[210:213], v[220:223], v[190:193]
	v_mfma_f32_16x16x32_f16 v[76:79], v[210:213], v[228:231], v[76:79]
	ds_read_b128 v[210:213], v136 offset:51200
	v_mfma_f32_16x16x32_f16 v[154:157], v[224:227], v[198:201], v[154:157]
	v_mfma_f32_16x16x32_f16 v[162:165], v[224:227], v[206:209], v[162:165]
	v_mfma_f32_16x16x32_f16 v[64:67], v[232:235], v[198:201], v[64:67]
	ds_read_b128 v[198:201], v133 offset:16384
	v_mfma_f32_16x16x32_f16 v[72:75], v[232:235], v[206:209], v[72:75]
	ds_read_b128 v[206:209], v133 offset:18432
	v_mfma_f32_16x16x32_f16 v[194:197], v[224:227], v[220:223], v[194:197]
	v_and_b32_e32 v30, 7, v148
	v_bfe_u32 v31, v148, 4, 3
	v_xor_b32_e32 v31, v31, v30
	v_sub_u32_e32 v31, v31, v30
	v_lshlrev_b32_e32 v30, 4, v31
	v_add_u32_e32 v30, 0x200, v30
	v_ashrrev_i32_e32 v31, 31, v30
	v_mfma_f32_16x16x32_f16 v[84:87], v[224:227], v[228:231], v[84:87]
	ds_read_b128 v[224:227], v136 offset:53248
	v_mfma_f32_16x16x32_f16 v[80:83], v[232:235], v[220:223], v[80:83]
	ds_read_b128 v[220:223], v133 offset:20480
	v_mfma_f32_16x16x32_f16 v[88:91], v[232:235], v[228:231], v[88:91]
	ds_read_b128 v[228:231], v133 offset:22528
	s_waitcnt lgkmcnt(4)
	v_mfma_f32_16x16x32_f16 v[138:141], v[202:205], v[198:201], v[138:141]
	ds_read_b128 v[232:235], v136 offset:55296
	s_waitcnt lgkmcnt(4)
	v_mfma_f32_16x16x32_f16 v[92:95], v[202:205], v[206:209], v[92:95]
	v_lshl_add_u64 v[0:1], v[108:109], 0, v[30:31]
	s_mov_b32 m0, s60
	s_nop 0
	global_load_lds_dwordx4 v[0:1], off
	v_mfma_f32_16x16x32_f16 v[142:145], v[210:213], v[198:201], v[142:145]
	v_lshl_add_u64 v[4:5], v[110:111], 0, v[30:31]
	s_mov_b32 m0, s68
	s_nop 0
	global_load_lds_dwordx4 v[4:5], off
	v_mfma_f32_16x16x32_f16 v[158:161], v[210:213], v[206:209], v[158:161]
	v_lshl_add_u64 v[8:9], v[112:113], 0, v[30:31]
	s_mov_b32 m0, s72
	s_nop 0
	global_load_lds_dwordx4 v[8:9], off
	s_waitcnt lgkmcnt(2)
	v_mfma_f32_16x16x32_f16 v[166:169], v[202:205], v[220:223], v[166:169]
	v_lshl_add_u64 v[12:13], v[114:115], 0, v[30:31]
	s_mov_b32 m0, s64
	s_nop 0
	global_load_lds_dwordx4 v[12:13], off
	s_waitcnt lgkmcnt(1)
	v_mfma_f32_16x16x32_f16 v[68:71], v[202:205], v[228:231], v[68:71]
	ds_read_b128 v[202:205], v135 offset:49152
	v_mfma_f32_16x16x32_f16 v[190:193], v[210:213], v[220:223], v[190:193]
	v_lshl_add_u64 v[16:17], v[116:117], 0, v[30:31]
	s_mov_b32 m0, s62
	s_nop 0
	global_load_lds_dwordx4 v[16:17], off
	v_mfma_f32_16x16x32_f16 v[76:79], v[210:213], v[228:231], v[76:79]
	ds_read_b128 v[210:213], v135 offset:51200
	v_mfma_f32_16x16x32_f16 v[154:157], v[224:227], v[198:201], v[154:157]
	v_lshl_add_u64 v[20:21], v[118:119], 0, v[30:31]
	s_mov_b32 m0, s70
	s_nop 0
	global_load_lds_dwordx4 v[20:21], off
	v_mfma_f32_16x16x32_f16 v[162:165], v[224:227], v[206:209], v[162:165]
	v_lshl_add_u64 v[24:25], v[120:121], 0, v[30:31]
	s_mov_b32 m0, s74
	s_nop 0
	global_load_lds_dwordx4 v[24:25], off
	s_waitcnt lgkmcnt(2)
	v_mfma_f32_16x16x32_f16 v[64:67], v[232:235], v[198:201], v[64:67]
	ds_read_b128 v[198:201], v134 offset:16384
	v_mfma_f32_16x16x32_f16 v[72:75], v[232:235], v[206:209], v[72:75]
	ds_read_b128 v[206:209], v134 offset:18432
	v_mfma_f32_16x16x32_f16 v[194:197], v[224:227], v[220:223], v[194:197]
	v_lshl_add_u64 v[28:29], v[122:123], 0, v[30:31]
	s_mov_b32 m0, s66
	s_nop 0
	global_load_lds_dwordx4 v[28:29], off
	v_mfma_f32_16x16x32_f16 v[84:87], v[224:227], v[228:231], v[84:87]
	ds_read_b128 v[224:227], v135 offset:53248
	v_mfma_f32_16x16x32_f16 v[80:83], v[232:235], v[220:223], v[80:83]
	ds_read_b128 v[220:223], v134 offset:20480
	v_mfma_f32_16x16x32_f16 v[88:91], v[232:235], v[228:231], v[88:91]
	ds_read_b128 v[228:231], v134 offset:22528
	ds_read_b128 v[232:235], v135 offset:55296
	s_waitcnt vmcnt(0) lgkmcnt(0)
	s_barrier
	v_mfma_f32_16x16x32_f16 v[138:141], v[202:205], v[198:201], v[138:141]
	v_mfma_f32_16x16x32_f16 v[92:95], v[202:205], v[206:209], v[92:95]
	v_mfma_f32_16x16x32_f16 v[142:145], v[210:213], v[198:201], v[142:145]
	v_mfma_f32_16x16x32_f16 v[158:161], v[210:213], v[206:209], v[158:161]
	v_mfma_f32_16x16x32_f16 v[166:169], v[202:205], v[220:223], v[166:169]
	v_mfma_f32_16x16x32_f16 v[68:71], v[202:205], v[228:231], v[68:71]
	ds_read_b128 v[202:205], v136 offset:32768
	v_mfma_f32_16x16x32_f16 v[190:193], v[210:213], v[220:223], v[190:193]
	v_mfma_f32_16x16x32_f16 v[76:79], v[210:213], v[228:231], v[76:79]
	ds_read_b128 v[210:213], v136 offset:34816
	v_mfma_f32_16x16x32_f16 v[154:157], v[224:227], v[198:201], v[154:157]
	v_mfma_f32_16x16x32_f16 v[162:165], v[224:227], v[206:209], v[162:165]
	v_mfma_f32_16x16x32_f16 v[64:67], v[232:235], v[198:201], v[64:67]
	ds_read_b128 v[198:201], v133
	v_mfma_f32_16x16x32_f16 v[72:75], v[232:235], v[206:209], v[72:75]
	ds_read_b128 v[206:209], v133 offset:2048
	v_mfma_f32_16x16x32_f16 v[194:197], v[224:227], v[220:223], v[194:197]
	v_and_b32_e32 v62, 7, v148
	v_bfe_u32 v63, v148, 4, 3
	v_xor_b32_e32 v63, v63, v62
	v_sub_u32_e32 v63, v63, v62
	v_lshlrev_b32_e32 v62, 4, v63
	v_add_u32_e32 v62, 0x280, v62
	v_ashrrev_i32_e32 v63, 31, v62
	v_mfma_f32_16x16x32_f16 v[84:87], v[224:227], v[228:231], v[84:87]
	ds_read_b128 v[224:227], v136 offset:36864
	v_mfma_f32_16x16x32_f16 v[80:83], v[232:235], v[220:223], v[80:83]
	ds_read_b128 v[220:223], v133 offset:4096
	v_mfma_f32_16x16x32_f16 v[88:91], v[232:235], v[228:231], v[88:91]
	ds_read_b128 v[228:231], v133 offset:6144
	s_waitcnt lgkmcnt(4)
; #define GL_LOAD(s_, kt_) if (VAR != 1) { a##s_##0 = GL_A(0, kt_); a##s_##1 = GL_A(1, kt_); a##s_##2 = GL_A(2, kt_); a##s_##3 = GL_A(3, kt_); b##s_##0 = GL_B(0, kt_); b##s_##1 = GL_B(1, kt_); b##s_##2 = GL_B(2, kt_); b##s_##3 = GL_B(3, kt_); }
; #define LDS_STORE(s_, buf_) if (VAR != 2) { LDS_ST1(sA, 0, buf_, a##s_##0) LDS_ST1(sA, 1, buf_, a##s_##1) LDS_ST1(sA, 2, buf_, a##s_##2) LDS_ST1(sA, 3, buf_, a##s_##3) LDS_ST1(sB, 0, buf_, b##s_##0) LDS_ST1(sB, 1, buf_, b##s_##1) LDS_ST1(sB, 2, buf_, b##s_##2) LDS_ST1(sB, 3, buf_, b##s_##3) }
;     ...
;   GL_LOAD(0, 0)
;   GL_LOAD(1, 1)
;   LDS_STORE(0, 0)
;   if (VAR != 4) __syncthreads();
; #pragma unroll
;   for (int kt = 0; kt < nk; kt += 2) {
;     if (kt + 2 < nk) { GL_LOAD(0, kt + 2) }
;     MMA_TILE(0)
;     LDS_STORE(1, 1)
;     if (VAR != 4) __syncthreads();
;     if (kt + 3 < nk) { GL_LOAD(1, kt + 3) }
;     MMA_TILE(1)
;     if (kt + 2 < nk) { LDS_STORE(0, 0) }
;     if (VAR != 4) __syncthreads();
	v_mfma_f32_16x16x32_f16 v[138:141], v[202:205], v[198:201], v[138:141]
	ds_read_b128 v[232:235], v136 offset:38912
	s_waitcnt lgkmcnt(4)
	v_mfma_f32_16x16x32_f16 v[92:95], v[202:205], v[206:209], v[92:95]
	v_lshl_add_u64 v[32:33], v[108:109], 0, v[62:63]
	s_mov_b32 m0, s61
	s_nop 0
	global_load_lds_dwordx4 v[32:33], off
	v_mfma_f32_16x16x32_f16 v[142:145], v[210:213], v[198:201], v[142:145]
	v_lshl_add_u64 v[36:37], v[110:111], 0, v[62:63]
	s_mov_b32 m0, s69
	s_nop 0
	global_load_lds_dwordx4 v[36:37], off
	v_mfma_f32_16x16x32_f16 v[158:161], v[210:213], v[206:209], v[158:161]
	v_lshl_add_u64 v[40:41], v[112:113], 0, v[62:63]
	s_mov_b32 m0, s73
	s_nop 0
	global_load_lds_dwordx4 v[40:41], off
	s_waitcnt lgkmcnt(2)
	v_mfma_f32_16x16x32_f16 v[166:169], v[202:205], v[220:223], v[166:169]
	v_lshl_add_u64 v[44:45], v[114:115], 0, v[62:63]
	s_mov_b32 m0, s65
	s_nop 0
	global_load_lds_dwordx4 v[44:45], off
	s_waitcnt lgkmcnt(1)
	v_mfma_f32_16x16x32_f16 v[68:71], v[202:205], v[228:231], v[68:71]
	ds_read_b128 v[202:205], v135 offset:32768
	v_mfma_f32_16x16x32_f16 v[190:193], v[210:213], v[220:223], v[190:193]
	v_lshl_add_u64 v[48:49], v[116:117], 0, v[62:63]
	s_mov_b32 m0, s63
	s_nop 0
	global_load_lds_dwordx4 v[48:49], off
	v_mfma_f32_16x16x32_f16 v[76:79], v[210:213], v[228:231], v[76:79]
	ds_read_b128 v[210:213], v135 offset:34816
	v_mfma_f32_16x16x32_f16 v[154:157], v[224:227], v[198:201], v[154:157]
	v_lshl_add_u64 v[52:53], v[118:119], 0, v[62:63]
	s_mov_b32 m0, s71
	s_nop 0
	global_load_lds_dwordx4 v[52:53], off
	v_mfma_f32_16x16x32_f16 v[162:165], v[224:227], v[206:209], v[162:165]
	v_lshl_add_u64 v[56:57], v[120:121], 0, v[62:63]
	s_mov_b32 m0, s75
	s_nop 0
	global_load_lds_dwordx4 v[56:57], off
	s_waitcnt lgkmcnt(2)
	v_mfma_f32_16x16x32_f16 v[64:67], v[232:235], v[198:201], v[64:67]
	ds_read_b128 v[198:201], v134
	v_mfma_f32_16x16x32_f16 v[72:75], v[232:235], v[206:209], v[72:75]
	ds_read_b128 v[206:209], v134 offset:2048
	v_mfma_f32_16x16x32_f16 v[194:197], v[224:227], v[220:223], v[194:197]
	v_lshl_add_u64 v[60:61], v[122:123], 0, v[62:63]
	s_mov_b32 m0, s67
	s_nop 0
	global_load_lds_dwordx4 v[60:61], off
	v_mfma_f32_16x16x32_f16 v[84:87], v[224:227], v[228:231], v[84:87]
	ds_read_b128 v[224:227], v135 offset:36864
	v_mfma_f32_16x16x32_f16 v[80:83], v[232:235], v[220:223], v[80:83]
	ds_read_b128 v[220:223], v134 offset:4096
	v_mfma_f32_16x16x32_f16 v[88:91], v[232:235], v[228:231], v[88:91]
	ds_read_b128 v[228:231], v134 offset:6144
	ds_read_b128 v[232:235], v135 offset:38912
	s_waitcnt vmcnt(0) lgkmcnt(0)
	s_barrier
	v_mfma_f32_16x16x32_f16 v[138:141], v[202:205], v[198:201], v[138:141]
	v_mfma_f32_16x16x32_f16 v[92:95], v[202:205], v[206:209], v[92:95]
	v_mfma_f32_16x16x32_f16 v[142:145], v[210:213], v[198:201], v[142:145]
	v_mfma_f32_16x16x32_f16 v[158:161], v[210:213], v[206:209], v[158:161]
	v_mfma_f32_16x16x32_f16 v[166:169], v[202:205], v[220:223], v[166:169]
	v_mfma_f32_16x16x32_f16 v[68:71], v[202:205], v[228:231], v[68:71]
	ds_read_b128 v[202:205], v136 offset:49152
	v_mfma_f32_16x16x32_f16 v[190:193], v[210:213], v[220:223], v[190:193]
	v_mfma_f32_16x16x32_f16 v[76:79], v[210:213], v[228:231], v[76:79]
	ds_read_b128 v[210:213], v136 offset:51200
	v_mfma_f32_16x16x32_f16 v[154:157], v[224:227], v[198:201], v[154:157]
	v_mfma_f32_16x16x32_f16 v[162:165], v[224:227], v[206:209], v[162:165]
	v_mfma_f32_16x16x32_f16 v[64:67], v[232:235], v[198:201], v[64:67]
	ds_read_b128 v[198:201], v133 offset:16384
	v_mfma_f32_16x16x32_f16 v[72:75], v[232:235], v[206:209], v[72:75]
	ds_read_b128 v[206:209], v133 offset:18432
	v_mfma_f32_16x16x32_f16 v[194:197], v[224:227], v[220:223], v[194:197]
	v_and_b32_e32 v30, 7, v148
	v_bfe_u32 v31, v148, 4, 3
	v_xor_b32_e32 v31, v31, v30
	v_sub_u32_e32 v31, v31, v30
	v_lshlrev_b32_e32 v30, 4, v31
	v_add_u32_e32 v30, 0x300, v30
	v_ashrrev_i32_e32 v31, 31, v30
	v_mfma_f32_16x16x32_f16 v[84:87], v[224:227], v[228:231], v[84:87]
	ds_read_b128 v[224:227], v136 offset:53248
	v_mfma_f32_16x16x32_f16 v[80:83], v[232:235], v[220:223], v[80:83]
	ds_read_b128 v[220:223], v133 offset:20480
	v_mfma_f32_16x16x32_f16 v[88:91], v[232:235], v[228:231], v[88:91]
	ds_read_b128 v[228:231], v133 offset:22528
	s_waitcnt lgkmcnt(4)
	v_mfma_f32_16x16x32_f16 v[138:141], v[202:205], v[198:201], v[138:141]
	ds_read_b128 v[232:235], v136 offset:55296
	s_waitcnt lgkmcnt(4)
	v_mfma_f32_16x16x32_f16 v[92:95], v[202:205], v[206:209], v[92:95]
	v_lshl_add_u64 v[0:1], v[108:109], 0, v[30:31]
	s_mov_b32 m0, s60
	s_nop 0
	global_load_lds_dwordx4 v[0:1], off
	v_mfma_f32_16x16x32_f16 v[142:145], v[210:213], v[198:201], v[142:145]
	v_lshl_add_u64 v[4:5], v[110:111], 0, v[30:31]
	s_mov_b32 m0, s68
	s_nop 0
	global_load_lds_dwordx4 v[4:5], off
	v_mfma_f32_16x16x32_f16 v[158:161], v[210:213], v[206:209], v[158:161]
	v_lshl_add_u64 v[8:9], v[112:113], 0, v[30:31]
	s_mov_b32 m0, s72
	s_nop 0
	global_load_lds_dwordx4 v[8:9], off
	s_waitcnt lgkmcnt(2)
	v_mfma_f32_16x16x32_f16 v[166:169], v[202:205], v[220:223], v[166:169]
	v_lshl_add_u64 v[12:13], v[114:115], 0, v[30:31]
	s_mov_b32 m0, s64
	s_nop 0
	global_load_lds_dwordx4 v[12:13], off
	s_waitcnt lgkmcnt(1)
	v_mfma_f32_16x16x32_f16 v[68:71], v[202:205], v[228:231], v[68:71]
	ds_read_b128 v[202:205], v135 offset:49152
	v_mfma_f32_16x16x32_f16 v[190:193], v[210:213], v[220:223], v[190:193]
	v_lshl_add_u64 v[16:17], v[116:117], 0, v[30:31]
	s_mov_b32 m0, s62
	s_nop 0
	global_load_lds_dwordx4 v[16:17], off
	v_mfma_f32_16x16x32_f16 v[76:79], v[210:213], v[228:231], v[76:79]
	ds_read_b128 v[210:213], v135 offset:51200
	v_mfma_f32_16x16x32_f16 v[154:157], v[224:227], v[198:201], v[154:157]
	v_lshl_add_u64 v[20:21], v[118:119], 0, v[30:31]
	s_mov_b32 m0, s70
	s_nop 0
	global_load_lds_dwordx4 v[20:21], off
	v_mfma_f32_16x16x32_f16 v[162:165], v[224:227], v[206:209], v[162:165]
	v_lshl_add_u64 v[24:25], v[120:121], 0, v[30:31]
	s_mov_b32 m0, s74
	s_nop 0
	global_load_lds_dwordx4 v[24:25], off
	s_waitcnt lgkmcnt(2)
	v_mfma_f32_16x16x32_f16 v[64:67], v[232:235], v[198:201], v[64:67]
	ds_read_b128 v[198:201], v134 offset:16384
	v_mfma_f32_16x16x32_f16 v[72:75], v[232:235], v[206:209], v[72:75]
	ds_read_b128 v[206:209], v134 offset:18432
	v_mfma_f32_16x16x32_f16 v[194:197], v[224:227], v[220:223], v[194:197]
	v_lshl_add_u64 v[28:29], v[122:123], 0, v[30:31]
	s_mov_b32 m0, s66
	s_nop 0
	global_load_lds_dwordx4 v[28:29], off
	v_mfma_f32_16x16x32_f16 v[84:87], v[224:227], v[228:231], v[84:87]
	ds_read_b128 v[224:227], v135 offset:53248
	v_mfma_f32_16x16x32_f16 v[80:83], v[232:235], v[220:223], v[80:83]
	ds_read_b128 v[220:223], v134 offset:20480
	v_mfma_f32_16x16x32_f16 v[88:91], v[232:235], v[228:231], v[88:91]
	ds_read_b128 v[228:231], v134 offset:22528
	ds_read_b128 v[232:235], v135 offset:55296
	s_waitcnt vmcnt(0) lgkmcnt(0)
	s_barrier
; #define GL_LOAD(s_, kt_) if (VAR != 1) { a##s_##0 = GL_A(0, kt_); a##s_##1 = GL_A(1, kt_); a##s_##2 = GL_A(2, kt_); a##s_##3 = GL_A(3, kt_); b##s_##0 = GL_B(0, kt_); b##s_##1 = GL_B(1, kt_); b##s_##2 = GL_B(2, kt_); b##s_##3 = GL_B(3, kt_); }
; #define LDS_STORE(s_, buf_) if (VAR != 2) { LDS_ST1(sA, 0, buf_, a##s_##0) LDS_ST1(sA, 1, buf_, a##s_##1) LDS_ST1(sA, 2, buf_, a##s_##2) LDS_ST1(sA, 3, buf_, a##s_##3) LDS_ST1(sB, 0, buf_, b##s_##0) LDS_ST1(sB, 1, buf_, b##s_##1) LDS_ST1(sB, 2, buf_, b##s_##2) LDS_ST1(sB, 3, buf_, b##s_##3) }
;     ...
;   GL_LOAD(0, 0)
;   GL_LOAD(1, 1)
;   LDS_STORE(0, 0)
;   if (VAR != 4) __syncthreads();
; #pragma unroll
;   for (int kt = 0; kt < nk; kt += 2) {
;     if (kt + 2 < nk) { GL_LOAD(0, kt + 2) }
;     MMA_TILE(0)
;     LDS_STORE(1, 1)
;     if (VAR != 4) __syncthreads();
;     if (kt + 3 < nk) { GL_LOAD(1, kt + 3) }
;     MMA_TILE(1)
;     if (kt + 2 < nk) { LDS_STORE(0, 0) }
;     if (VAR != 4) __syncthreads();
	v_mfma_f32_16x16x32_f16 v[138:141], v[202:205], v[198:201], v[138:141]
	v_mfma_f32_16x16x32_f16 v[92:95], v[202:205], v[206:209], v[92:95]
	v_mfma_f32_16x16x32_f16 v[142:145], v[210:213], v[198:201], v[142:145]
	v_mfma_f32_16x16x32_f16 v[158:161], v[210:213], v[206:209], v[158:161]
	v_mfma_f32_16x16x32_f16 v[166:169], v[202:205], v[220:223], v[166:169]
	v_mfma_f32_16x16x32_f16 v[68:71], v[202:205], v[228:231], v[68:71]
	ds_read_b128 v[202:205], v136 offset:32768
	v_mfma_f32_16x16x32_f16 v[190:193], v[210:213], v[220:223], v[190:193]
	v_mfma_f32_16x16x32_f16 v[76:79], v[210:213], v[228:231], v[76:79]
	ds_read_b128 v[210:213], v136 offset:34816
	v_mfma_f32_16x16x32_f16 v[154:157], v[224:227], v[198:201], v[154:157]
	v_mfma_f32_16x16x32_f16 v[162:165], v[224:227], v[206:209], v[162:165]
	v_mfma_f32_16x16x32_f16 v[64:67], v[232:235], v[198:201], v[64:67]
	ds_read_b128 v[198:201], v133
	v_mfma_f32_16x16x32_f16 v[72:75], v[232:235], v[206:209], v[72:75]
	ds_read_b128 v[206:209], v133 offset:2048
	v_mfma_f32_16x16x32_f16 v[194:197], v[224:227], v[220:223], v[194:197]
	v_and_b32_e32 v62, 7, v148
	v_bfe_u32 v63, v148, 4, 3
	v_xor_b32_e32 v63, v63, v62
	v_sub_u32_e32 v63, v63, v62
	v_lshlrev_b32_e32 v62, 4, v63
	v_add_u32_e32 v62, 0x380, v62
	v_ashrrev_i32_e32 v63, 31, v62
	v_mfma_f32_16x16x32_f16 v[84:87], v[224:227], v[228:231], v[84:87]
	ds_read_b128 v[224:227], v136 offset:36864
	v_mfma_f32_16x16x32_f16 v[80:83], v[232:235], v[220:223], v[80:83]
	ds_read_b128 v[220:223], v133 offset:4096
	v_mfma_f32_16x16x32_f16 v[88:91], v[232:235], v[228:231], v[88:91]
	ds_read_b128 v[228:231], v133 offset:6144
	s_waitcnt lgkmcnt(4)
	v_mfma_f32_16x16x32_f16 v[138:141], v[202:205], v[198:201], v[138:141]
	ds_read_b128 v[232:235], v136 offset:38912
	s_waitcnt lgkmcnt(4)
	v_mfma_f32_16x16x32_f16 v[92:95], v[202:205], v[206:209], v[92:95]
	v_lshl_add_u64 v[32:33], v[108:109], 0, v[62:63]
	s_mov_b32 m0, s61
	s_nop 0
	global_load_lds_dwordx4 v[32:33], off
	v_mfma_f32_16x16x32_f16 v[142:145], v[210:213], v[198:201], v[142:145]
	v_lshl_add_u64 v[36:37], v[110:111], 0, v[62:63]
	s_mov_b32 m0, s69
	s_nop 0
	global_load_lds_dwordx4 v[36:37], off
	v_mfma_f32_16x16x32_f16 v[158:161], v[210:213], v[206:209], v[158:161]
	v_lshl_add_u64 v[40:41], v[112:113], 0, v[62:63]
	s_mov_b32 m0, s73
	s_nop 0
	global_load_lds_dwordx4 v[40:41], off
	s_waitcnt lgkmcnt(2)
	v_mfma_f32_16x16x32_f16 v[166:169], v[202:205], v[220:223], v[166:169]
	v_lshl_add_u64 v[44:45], v[114:115], 0, v[62:63]
	s_mov_b32 m0, s65
	s_nop 0
	global_load_lds_dwordx4 v[44:45], off
	s_waitcnt lgkmcnt(1)
	v_mfma_f32_16x16x32_f16 v[68:71], v[202:205], v[228:231], v[68:71]
	ds_read_b128 v[202:205], v135 offset:32768
	v_mfma_f32_16x16x32_f16 v[190:193], v[210:213], v[220:223], v[190:193]
	v_lshl_add_u64 v[48:49], v[116:117], 0, v[62:63]
	s_mov_b32 m0, s63
	s_nop 0
	global_load_lds_dwordx4 v[48:49], off
	v_mfma_f32_16x16x32_f16 v[76:79], v[210:213], v[228:231], v[76:79]
	ds_read_b128 v[210:213], v135 offset:34816
	v_mfma_f32_16x16x32_f16 v[154:157], v[224:227], v[198:201], v[154:157]
	v_lshl_add_u64 v[52:53], v[118:119], 0, v[62:63]
	s_mov_b32 m0, s71
	s_nop 0
	global_load_lds_dwordx4 v[52:53], off
	v_mfma_f32_16x16x32_f16 v[162:165], v[224:227], v[206:209], v[162:165]
	v_lshl_add_u64 v[56:57], v[120:121], 0, v[62:63]
	s_mov_b32 m0, s75
	s_nop 0
	global_load_lds_dwordx4 v[56:57], off
	s_waitcnt lgkmcnt(2)
	v_mfma_f32_16x16x32_f16 v[64:67], v[232:235], v[198:201], v[64:67]
	ds_read_b128 v[198:201], v134
	v_mfma_f32_16x16x32_f16 v[72:75], v[232:235], v[206:209], v[72:75]
	ds_read_b128 v[206:209], v134 offset:2048
	v_mfma_f32_16x16x32_f16 v[194:197], v[224:227], v[220:223], v[194:197]
	v_lshl_add_u64 v[60:61], v[122:123], 0, v[62:63]
	s_mov_b32 m0, s67
	s_nop 0
	global_load_lds_dwordx4 v[60:61], off
	v_mfma_f32_16x16x32_f16 v[84:87], v[224:227], v[228:231], v[84:87]
	ds_read_b128 v[224:227], v135 offset:36864
	v_mfma_f32_16x16x32_f16 v[80:83], v[232:235], v[220:223], v[80:83]
	ds_read_b128 v[220:223], v134 offset:4096
	v_mfma_f32_16x16x32_f16 v[88:91], v[232:235], v[228:231], v[88:91]
	ds_read_b128 v[228:231], v134 offset:6144
	ds_read_b128 v[232:235], v135 offset:38912
	s_waitcnt vmcnt(0) lgkmcnt(0)
	s_barrier
	v_mfma_f32_16x16x32_f16 v[138:141], v[202:205], v[198:201], v[138:141]
	v_mfma_f32_16x16x32_f16 v[92:95], v[202:205], v[206:209], v[92:95]
	v_mfma_f32_16x16x32_f16 v[142:145], v[210:213], v[198:201], v[142:145]
	v_mfma_f32_16x16x32_f16 v[158:161], v[210:213], v[206:209], v[158:161]
	v_mfma_f32_16x16x32_f16 v[166:169], v[202:205], v[220:223], v[166:169]
	v_mfma_f32_16x16x32_f16 v[68:71], v[202:205], v[228:231], v[68:71]
	ds_read_b128 v[202:205], v136 offset:49152
	v_mfma_f32_16x16x32_f16 v[190:193], v[210:213], v[220:223], v[190:193]
	v_mfma_f32_16x16x32_f16 v[76:79], v[210:213], v[228:231], v[76:79]
	ds_read_b128 v[210:213], v136 offset:51200
	v_mfma_f32_16x16x32_f16 v[154:157], v[224:227], v[198:201], v[154:157]
	v_mfma_f32_16x16x32_f16 v[162:165], v[224:227], v[206:209], v[162:165]
	v_mfma_f32_16x16x32_f16 v[64:67], v[232:235], v[198:201], v[64:67]
	ds_read_b128 v[198:201], v133 offset:16384
	v_mfma_f32_16x16x32_f16 v[72:75], v[232:235], v[206:209], v[72:75]
	ds_read_b128 v[206:209], v133 offset:18432
	v_mfma_f32_16x16x32_f16 v[194:197], v[224:227], v[220:223], v[194:197]
	v_and_b32_e32 v30, 7, v148
	v_bfe_u32 v31, v148, 4, 3
	v_xor_b32_e32 v31, v31, v30
	v_sub_u32_e32 v31, v31, v30
	v_lshlrev_b32_e32 v30, 4, v31
	v_add_u32_e32 v30, 0x400, v30
	v_ashrrev_i32_e32 v31, 31, v30
	v_mfma_f32_16x16x32_f16 v[84:87], v[224:227], v[228:231], v[84:87]
	ds_read_b128 v[224:227], v136 offset:53248
	v_mfma_f32_16x16x32_f16 v[80:83], v[232:235], v[220:223], v[80:83]
	ds_read_b128 v[220:223], v133 offset:20480
	v_mfma_f32_16x16x32_f16 v[88:91], v[232:235], v[228:231], v[88:91]
	ds_read_b128 v[228:231], v133 offset:22528
	s_waitcnt lgkmcnt(4)
; #define GL_LOAD(s_, kt_) if (VAR != 1) { a##s_##0 = GL_A(0, kt_); a##s_##1 = GL_A(1, kt_); a##s_##2 = GL_A(2, kt_); a##s_##3 = GL_A(3, kt_); b##s_##0 = GL_B(0, kt_); b##s_##1 = GL_B(1, kt_); b##s_##2 = GL_B(2, kt_); b##s_##3 = GL_B(3, kt_); }
; #define LDS_STORE(s_, buf_) if (VAR != 2) { LDS_ST1(sA, 0, buf_, a##s_##0) LDS_ST1(sA, 1, buf_, a##s_##1) LDS_ST1(sA, 2, buf_, a##s_##2) LDS_ST1(sA, 3, buf_, a##s_##3) LDS_ST1(sB, 0, buf_, b##s_##0) LDS_ST1(sB, 1, buf_, b##s_##1) LDS_ST1(sB, 2, buf_, b##s_##2) LDS_ST1(sB, 3, buf_, b##s_##3) }
;     ...
;   GL_LOAD(0, 0)
;   GL_LOAD(1, 1)
;   LDS_STORE(0, 0)
;   if (VAR != 4) __syncthreads();
; #pragma unroll
;   for (int kt = 0; kt < nk; kt += 2) {
;     if (kt + 2 < nk) { GL_LOAD(0, kt + 2) }
;     MMA_TILE(0)
;     LDS_STORE(1, 1)
;     if (VAR != 4) __syncthreads();
;     if (kt + 3 < nk) { GL_LOAD(1, kt + 3) }
;     MMA_TILE(1)
;     if (kt + 2 < nk) { LDS_STORE(0, 0) }
;     if (VAR != 4) __syncthreads();
	v_mfma_f32_16x16x32_f16 v[138:141], v[202:205], v[198:201], v[138:141]
	ds_read_b128 v[232:235], v136 offset:55296
	s_waitcnt lgkmcnt(4)
	v_mfma_f32_16x16x32_f16 v[92:95], v[202:205], v[206:209], v[92:95]
	v_lshl_add_u64 v[0:1], v[108:109], 0, v[30:31]
	s_mov_b32 m0, s60
	s_nop 0
	global_load_lds_dwordx4 v[0:1], off
	v_mfma_f32_16x16x32_f16 v[142:145], v[210:213], v[198:201], v[142:145]
	v_lshl_add_u64 v[4:5], v[110:111], 0, v[30:31]
	s_mov_b32 m0, s68
	s_nop 0
	global_load_lds_dwordx4 v[4:5], off
	v_mfma_f32_16x16x32_f16 v[158:161], v[210:213], v[206:209], v[158:161]
	v_lshl_add_u64 v[8:9], v[112:113], 0, v[30:31]
	s_mov_b32 m0, s72
	s_nop 0
	global_load_lds_dwordx4 v[8:9], off
	s_waitcnt lgkmcnt(2)
	v_mfma_f32_16x16x32_f16 v[166:169], v[202:205], v[220:223], v[166:169]
	v_lshl_add_u64 v[12:13], v[114:115], 0, v[30:31]
	s_mov_b32 m0, s64
	s_nop 0
	global_load_lds_dwordx4 v[12:13], off
	s_waitcnt lgkmcnt(1)
	v_mfma_f32_16x16x32_f16 v[68:71], v[202:205], v[228:231], v[68:71]
	ds_read_b128 v[202:205], v135 offset:49152
	v_mfma_f32_16x16x32_f16 v[190:193], v[210:213], v[220:223], v[190:193]
	v_lshl_add_u64 v[16:17], v[116:117], 0, v[30:31]
	s_mov_b32 m0, s62
	s_nop 0
	global_load_lds_dwordx4 v[16:17], off
	v_mfma_f32_16x16x32_f16 v[76:79], v[210:213], v[228:231], v[76:79]
	ds_read_b128 v[210:213], v135 offset:51200
	v_mfma_f32_16x16x32_f16 v[154:157], v[224:227], v[198:201], v[154:157]
	v_lshl_add_u64 v[20:21], v[118:119], 0, v[30:31]
	s_mov_b32 m0, s70
	s_nop 0
	global_load_lds_dwordx4 v[20:21], off
	v_mfma_f32_16x16x32_f16 v[162:165], v[224:227], v[206:209], v[162:165]
	v_lshl_add_u64 v[24:25], v[120:121], 0, v[30:31]
	s_mov_b32 m0, s74
	s_nop 0
	global_load_lds_dwordx4 v[24:25], off
	s_waitcnt lgkmcnt(2)
	v_mfma_f32_16x16x32_f16 v[64:67], v[232:235], v[198:201], v[64:67]
	ds_read_b128 v[198:201], v134 offset:16384
	v_mfma_f32_16x16x32_f16 v[72:75], v[232:235], v[206:209], v[72:75]
	ds_read_b128 v[206:209], v134 offset:18432
	v_mfma_f32_16x16x32_f16 v[194:197], v[224:227], v[220:223], v[194:197]
	v_lshl_add_u64 v[28:29], v[122:123], 0, v[30:31]
	s_mov_b32 m0, s66
	s_nop 0
	global_load_lds_dwordx4 v[28:29], off
	v_mfma_f32_16x16x32_f16 v[84:87], v[224:227], v[228:231], v[84:87]
	ds_read_b128 v[224:227], v135 offset:53248
	v_mfma_f32_16x16x32_f16 v[80:83], v[232:235], v[220:223], v[80:83]
	ds_read_b128 v[220:223], v134 offset:20480
	v_mfma_f32_16x16x32_f16 v[88:91], v[232:235], v[228:231], v[88:91]
	ds_read_b128 v[228:231], v134 offset:22528
	s_waitcnt lgkmcnt(4)
	v_mfma_f32_16x16x32_f16 v[138:141], v[202:205], v[198:201], v[138:141]
	ds_read_b128 v[232:235], v135 offset:55296
	s_waitcnt vmcnt(0) lgkmcnt(0)
	s_barrier
	v_mfma_f32_16x16x32_f16 v[142:145], v[210:213], v[198:201], v[142:145]
	ds_read_b128 v[0:3], v133
	v_mfma_f32_16x16x32_f16 v[158:161], v[210:213], v[206:209], v[158:161]
	ds_read_b128 v[4:7], v136 offset:32768
	v_mfma_f32_16x16x32_f16 v[154:157], v[224:227], v[198:201], v[154:157]
	ds_read_b128 v[8:11], v133 offset:2048
	v_mfma_f32_16x16x32_f16 v[162:165], v[224:227], v[206:209], v[162:165]
	ds_read_b128 v[12:15], v136 offset:34816
	v_mfma_f32_16x16x32_f16 v[190:193], v[210:213], v[220:223], v[190:193]
	ds_read_b128 v[16:19], v133 offset:4096
	v_mfma_f32_16x16x32_f16 v[210:213], v[210:213], v[228:231], v[76:79]
	ds_read_b128 v[20:23], v136 offset:36864
	v_mfma_f32_16x16x32_f16 v[194:197], v[224:227], v[220:223], v[194:197]
	ds_read_b128 v[24:27], v133 offset:6144
	v_mfma_f32_16x16x32_f16 v[224:227], v[224:227], v[228:231], v[84:87]
	ds_read_b128 v[28:31], v136 offset:38912
	v_mfma_f32_16x16x32_f16 v[198:201], v[232:235], v[198:201], v[64:67]
	s_nop 2
	v_mfma_f32_16x16x32_f16 v[236:239], v[202:205], v[206:209], v[92:95]
	v_mfma_f32_16x16x32_f16 v[206:209], v[232:235], v[206:209], v[72:75]
	v_mfma_f32_16x16x32_f16 v[166:169], v[202:205], v[220:223], v[166:169]
	v_mfma_f32_16x16x32_f16 v[220:223], v[232:235], v[220:223], v[80:83]
	v_mfma_f32_16x16x32_f16 v[202:205], v[202:205], v[228:231], v[68:71]
	v_mfma_f32_16x16x32_f16 v[228:231], v[232:235], v[228:231], v[88:91]
	ds_read_b128 v[232:235], v135 offset:38912
	s_nop 0
	s_waitcnt lgkmcnt(7)
	v_mfma_f32_16x16x32_f16 v[138:141], v[4:7], v[0:3], v[138:141]
	s_waitcnt lgkmcnt(5)
	v_mfma_f32_16x16x32_f16 v[142:145], v[12:15], v[0:3], v[142:145]
	s_waitcnt lgkmcnt(3)
	v_mfma_f32_16x16x32_f16 v[154:157], v[20:23], v[0:3], v[154:157]
	s_waitcnt lgkmcnt(1)
	v_mfma_f32_16x16x32_f16 v[0:3], v[28:31], v[0:3], v[198:201]
	v_mfma_f32_16x16x32_f16 v[198:201], v[4:7], v[8:11], v[236:239]
	v_mfma_f32_16x16x32_f16 v[158:161], v[12:15], v[8:11], v[158:161]
	v_and_b32_e32 v62, 7, v148
	v_bfe_u32 v63, v148, 4, 3
	v_xor_b32_e32 v63, v63, v62
	v_sub_u32_e32 v63, v63, v62
	v_lshlrev_b32_e32 v62, 4, v63
	v_add_u32_e32 v62, 0x480, v62
	v_ashrrev_i32_e32 v63, 31, v62
	v_lshl_add_u64 v[32:33], v[108:109], 0, v[62:63]
	s_mov_b32 m0, s61
	s_nop 0
	global_load_lds_dwordx4 v[32:33], off
	v_mfma_f32_16x16x32_f16 v[166:169], v[4:7], v[16:19], v[166:169]
	v_lshl_add_u64 v[36:37], v[110:111], 0, v[62:63]
	s_mov_b32 m0, s69
	s_nop 0
	global_load_lds_dwordx4 v[36:37], off
	v_lshl_add_u64 v[40:41], v[112:113], 0, v[62:63]
	s_mov_b32 m0, s73
	s_nop 0
	global_load_lds_dwordx4 v[40:41], off
	v_mfma_f32_16x16x32_f16 v[4:7], v[4:7], v[24:27], v[202:205]
	s_nop 2
	ds_read_b128 v[202:205], v135 offset:32768
	v_lshl_add_u64 v[44:45], v[114:115], 0, v[62:63]
	s_mov_b32 m0, s65
	s_nop 0
	global_load_lds_dwordx4 v[44:45], off
	v_mfma_f32_16x16x32_f16 v[190:193], v[12:15], v[16:19], v[190:193]
	v_lshl_add_u64 v[48:49], v[116:117], 0, v[62:63]
	s_mov_b32 m0, s63
	s_nop 0
	global_load_lds_dwordx4 v[48:49], off
	v_mfma_f32_16x16x32_f16 v[12:15], v[12:15], v[24:27], v[210:213]
	s_nop 2
	ds_read_b128 v[210:213], v135 offset:34816
	v_lshl_add_u64 v[52:53], v[118:119], 0, v[62:63]
	s_mov_b32 m0, s71
	s_nop 0
	global_load_lds_dwordx4 v[52:53], off
	v_mfma_f32_16x16x32_f16 v[162:165], v[20:23], v[8:11], v[162:165]
	v_lshl_add_u64 v[56:57], v[120:121], 0, v[62:63]
	s_mov_b32 m0, s75
	s_nop 0
	global_load_lds_dwordx4 v[56:57], off
	v_lshl_add_u64 v[60:61], v[122:123], 0, v[62:63]
	s_mov_b32 m0, s67
	s_nop 0
	global_load_lds_dwordx4 v[60:61], off
	v_mfma_f32_16x16x32_f16 v[8:11], v[28:31], v[8:11], v[206:209]
	s_nop 2
	ds_read_b128 v[206:209], v134 offset:2048
	v_mfma_f32_16x16x32_f16 v[194:197], v[20:23], v[16:19], v[194:197]
	v_mfma_f32_16x16x32_f16 v[20:23], v[20:23], v[24:27], v[224:227]
	s_nop 2
	ds_read_b128 v[224:227], v135 offset:36864
	v_mfma_f32_16x16x32_f16 v[16:19], v[28:31], v[16:19], v[220:223]
	s_nop 2
	ds_read_b128 v[220:223], v134 offset:4096
	v_mfma_f32_16x16x32_f16 v[24:27], v[28:31], v[24:27], v[228:231]
	ds_read_b128 v[28:31], v134
	s_waitcnt lgkmcnt(0)
	v_mfma_f32_16x16x32_f16 v[138:141], v[202:205], v[28:31], v[138:141]
	ds_read_b128 v[228:231], v134 offset:6144
	s_waitcnt vmcnt(0) lgkmcnt(0)
	s_barrier
; #define GL_LOAD(s_, kt_) if (VAR != 1) { a##s_##0 = GL_A(0, kt_); a##s_##1 = GL_A(1, kt_); a##s_##2 = GL_A(2, kt_); a##s_##3 = GL_A(3, kt_); b##s_##0 = GL_B(0, kt_); b##s_##1 = GL_B(1, kt_); b##s_##2 = GL_B(2, kt_); b##s_##3 = GL_B(3, kt_); }
; #define LDS_STORE(s_, buf_) if (VAR != 2) { LDS_ST1(sA, 0, buf_, a##s_##0) LDS_ST1(sA, 1, buf_, a##s_##1) LDS_ST1(sA, 2, buf_, a##s_##2) LDS_ST1(sA, 3, buf_, a##s_##3) LDS_ST1(sB, 0, buf_, b##s_##0) LDS_ST1(sB, 1, buf_, b##s_##1) LDS_ST1(sB, 2, buf_, b##s_##2) LDS_ST1(sB, 3, buf_, b##s_##3) }
;     ...
;   GL_LOAD(0, 0)
;   GL_LOAD(1, 1)
;   LDS_STORE(0, 0)
;   if (VAR != 4) __syncthreads();
; #pragma unroll
;   for (int kt = 0; kt < nk; kt += 2) {
;     if (kt + 2 < nk) { GL_LOAD(0, kt + 2) }
;     MMA_TILE(0)
;     LDS_STORE(1, 1)
;     if (VAR != 4) __syncthreads();
;     if (kt + 3 < nk) { GL_LOAD(1, kt + 3) }
;     MMA_TILE(1)
;     if (kt + 2 < nk) { LDS_STORE(0, 0) }
;     if (VAR != 4) __syncthreads();
	v_mfma_f32_16x16x32_f16 v[142:145], v[210:213], v[28:31], v[142:145]
	ds_read_b128 v[32:35], v133 offset:16384
	v_mfma_f32_16x16x32_f16 v[158:161], v[210:213], v[206:209], v[158:161]
	ds_read_b128 v[36:39], v136 offset:49152
	v_mfma_f32_16x16x32_f16 v[154:157], v[224:227], v[28:31], v[154:157]
	ds_read_b128 v[40:43], v133 offset:18432
	v_mfma_f32_16x16x32_f16 v[162:165], v[224:227], v[206:209], v[162:165]
	ds_read_b128 v[44:47], v136 offset:51200
	v_mfma_f32_16x16x32_f16 v[190:193], v[210:213], v[220:223], v[190:193]
	ds_read_b128 v[48:51], v133 offset:20480
	v_mfma_f32_16x16x32_f16 v[210:213], v[210:213], v[228:231], v[12:15]
	ds_read_b128 v[52:55], v136 offset:53248
	v_mfma_f32_16x16x32_f16 v[194:197], v[224:227], v[220:223], v[194:197]
	ds_read_b128 v[56:59], v133 offset:22528
	v_mfma_f32_16x16x32_f16 v[224:227], v[224:227], v[228:231], v[20:23]
	ds_read_b128 v[60:63], v136 offset:55296
	v_mfma_f32_16x16x32_f16 v[236:239], v[232:235], v[28:31], v[0:3]
	v_mfma_f32_16x16x32_f16 v[198:201], v[202:205], v[206:209], v[198:201]
	v_mfma_f32_16x16x32_f16 v[206:209], v[232:235], v[206:209], v[8:11]
	v_mfma_f32_16x16x32_f16 v[166:169], v[202:205], v[220:223], v[166:169]
	v_mfma_f32_16x16x32_f16 v[220:223], v[232:235], v[220:223], v[16:19]
	v_mfma_f32_16x16x32_f16 v[202:205], v[202:205], v[228:231], v[4:7]
	v_mfma_f32_16x16x32_f16 v[228:231], v[232:235], v[228:231], v[24:27]
	ds_read_b128 v[232:235], v135 offset:55296
	s_nop 1
	s_waitcnt lgkmcnt(7)
	v_mfma_f32_16x16x32_f16 v[138:141], v[36:39], v[32:35], v[138:141]
	s_waitcnt lgkmcnt(6)
	v_mfma_f32_16x16x32_f16 v[198:201], v[36:39], v[40:43], v[198:201]
	s_waitcnt lgkmcnt(5)
	v_mfma_f32_16x16x32_f16 v[142:145], v[44:47], v[32:35], v[142:145]
	v_mfma_f32_16x16x32_f16 v[158:161], v[44:47], v[40:43], v[158:161]
	s_waitcnt lgkmcnt(4)
	v_mfma_f32_16x16x32_f16 v[166:169], v[36:39], v[48:51], v[166:169]
	v_and_b32_e32 v94, 7, v148
	v_bfe_u32 v95, v148, 4, 3
	v_xor_b32_e32 v95, v95, v94
	v_sub_u32_e32 v95, v95, v94
	v_lshlrev_b32_e32 v94, 4, v95
	v_add_u32_e32 v94, 0x500, v94
	v_ashrrev_i32_e32 v95, 31, v94
	s_waitcnt lgkmcnt(2)
	v_mfma_f32_16x16x32_f16 v[36:39], v[36:39], v[56:59], v[202:205]
	s_nop 2
	ds_read_b128 v[202:205], v135 offset:49152
	v_lshl_add_u64 v[64:65], v[108:109], 0, v[94:95]
	s_mov_b32 m0, s60
	s_nop 0
	global_load_lds_dwordx4 v[64:65], off
	v_mfma_f32_16x16x32_f16 v[190:193], v[44:47], v[48:51], v[190:193]
	v_lshl_add_u64 v[68:69], v[110:111], 0, v[94:95]
	s_mov_b32 m0, s68
	s_nop 0
	global_load_lds_dwordx4 v[68:69], off
	v_lshl_add_u64 v[72:73], v[112:113], 0, v[94:95]
	s_mov_b32 m0, s72
	s_nop 0
	global_load_lds_dwordx4 v[72:73], off
	v_mfma_f32_16x16x32_f16 v[44:47], v[44:47], v[56:59], v[210:213]
	s_nop 2
	ds_read_b128 v[210:213], v135 offset:51200
	v_mfma_f32_16x16x32_f16 v[154:157], v[52:55], v[32:35], v[154:157]
	v_lshl_add_u64 v[76:77], v[114:115], 0, v[94:95]
	s_mov_b32 m0, s64
	s_nop 0
	global_load_lds_dwordx4 v[76:77], off
	v_mfma_f32_16x16x32_f16 v[162:165], v[52:55], v[40:43], v[162:165]
	v_lshl_add_u64 v[80:81], v[116:117], 0, v[94:95]
	s_mov_b32 m0, s62
	s_nop 0
	global_load_lds_dwordx4 v[80:81], off
	s_waitcnt lgkmcnt(3)
	v_mfma_f32_16x16x32_f16 v[32:35], v[60:63], v[32:35], v[236:239]
	v_lshl_add_u64 v[84:85], v[118:119], 0, v[94:95]
	s_mov_b32 m0, s70
	s_nop 0
	global_load_lds_dwordx4 v[84:85], off
	v_mfma_f32_16x16x32_f16 v[40:43], v[60:63], v[40:43], v[206:209]
	s_nop 2
	ds_read_b128 v[206:209], v134 offset:18432
	v_mfma_f32_16x16x32_f16 v[194:197], v[52:55], v[48:51], v[194:197]
	v_lshl_add_u64 v[88:89], v[120:121], 0, v[94:95]
	s_mov_b32 m0, s74
	s_nop 0
	global_load_lds_dwordx4 v[88:89], off
	v_mfma_f32_16x16x32_f16 v[52:55], v[52:55], v[56:59], v[224:227]
	s_nop 2
	ds_read_b128 v[224:227], v135 offset:53248
	v_mfma_f32_16x16x32_f16 v[48:51], v[60:63], v[48:51], v[220:223]
	s_nop 2
	ds_read_b128 v[220:223], v134 offset:20480
	v_mfma_f32_16x16x32_f16 v[56:59], v[60:63], v[56:59], v[228:231]
	ds_read_b128 v[60:63], v134 offset:16384
	s_waitcnt lgkmcnt(0)
	v_mfma_f32_16x16x32_f16 v[138:141], v[202:205], v[60:63], v[138:141]
	ds_read_b128 v[228:231], v134 offset:22528
	v_lshl_add_u64 v[92:93], v[122:123], 0, v[94:95]
	s_mov_b32 m0, s66
	s_nop 0
	global_load_lds_dwordx4 v[92:93], off
	s_waitcnt vmcnt(0) lgkmcnt(0)
	s_barrier
; #define GL_LOAD(s_, kt_) if (VAR != 1) { a##s_##0 = GL_A(0, kt_); a##s_##1 = GL_A(1, kt_); a##s_##2 = GL_A(2, kt_); a##s_##3 = GL_A(3, kt_); b##s_##0 = GL_B(0, kt_); b##s_##1 = GL_B(1, kt_); b##s_##2 = GL_B(2, kt_); b##s_##3 = GL_B(3, kt_); }
; #define LDS_STORE(s_, buf_) if (VAR != 2) { LDS_ST1(sA, 0, buf_, a##s_##0) LDS_ST1(sA, 1, buf_, a##s_##1) LDS_ST1(sA, 2, buf_, a##s_##2) LDS_ST1(sA, 3, buf_, a##s_##3) LDS_ST1(sB, 0, buf_, b##s_##0) LDS_ST1(sB, 1, buf_, b##s_##1) LDS_ST1(sB, 2, buf_, b##s_##2) LDS_ST1(sB, 3, buf_, b##s_##3) }
;     ...
;   GL_LOAD(0, 0)
;   GL_LOAD(1, 1)
;   LDS_STORE(0, 0)
;   if (VAR != 4) __syncthreads();
; #pragma unroll
;   for (int kt = 0; kt < nk; kt += 2) {
;     if (kt + 2 < nk) { GL_LOAD(0, kt + 2) }
;     MMA_TILE(0)
;     LDS_STORE(1, 1)
;     if (VAR != 4) __syncthreads();
;     if (kt + 3 < nk) { GL_LOAD(1, kt + 3) }
;     MMA_TILE(1)
;     if (kt + 2 < nk) { LDS_STORE(0, 0) }
;     if (VAR != 4) __syncthreads();
	v_mfma_f32_16x16x32_f16 v[142:145], v[210:213], v[60:63], v[142:145]
	ds_read_b128 v[64:67], v133
	v_mfma_f32_16x16x32_f16 v[158:161], v[210:213], v[206:209], v[158:161]
	ds_read_b128 v[68:71], v136 offset:32768
	v_mfma_f32_16x16x32_f16 v[154:157], v[224:227], v[60:63], v[154:157]
	ds_read_b128 v[72:75], v133 offset:2048
	v_mfma_f32_16x16x32_f16 v[162:165], v[224:227], v[206:209], v[162:165]
	ds_read_b128 v[76:79], v136 offset:34816
	v_mfma_f32_16x16x32_f16 v[190:193], v[210:213], v[220:223], v[190:193]
	ds_read_b128 v[80:83], v133 offset:4096
	v_mfma_f32_16x16x32_f16 v[210:213], v[210:213], v[228:231], v[44:47]
	ds_read_b128 v[84:87], v136 offset:36864
	v_mfma_f32_16x16x32_f16 v[194:197], v[224:227], v[220:223], v[194:197]
	ds_read_b128 v[88:91], v133 offset:6144
	v_mfma_f32_16x16x32_f16 v[224:227], v[224:227], v[228:231], v[52:55]
	ds_read_b128 v[92:95], v136 offset:38912
	v_mfma_f32_16x16x32_f16 v[236:239], v[232:235], v[60:63], v[32:35]
	s_nop 0
	v_mfma_f32_16x16x32_f16 v[198:201], v[202:205], v[206:209], v[198:201]
	v_mfma_f32_16x16x32_f16 v[206:209], v[232:235], v[206:209], v[40:43]
	v_mfma_f32_16x16x32_f16 v[166:169], v[202:205], v[220:223], v[166:169]
	v_mfma_f32_16x16x32_f16 v[220:223], v[232:235], v[220:223], v[48:51]
	v_mfma_f32_16x16x32_f16 v[202:205], v[202:205], v[228:231], v[36:39]
	v_mfma_f32_16x16x32_f16 v[228:231], v[232:235], v[228:231], v[56:59]
	ds_read_b128 v[232:235], v135 offset:38912
	s_nop 1
	s_waitcnt lgkmcnt(7)
	v_mfma_f32_16x16x32_f16 v[138:141], v[68:71], v[64:67], v[138:141]
	s_waitcnt lgkmcnt(6)
	v_mfma_f32_16x16x32_f16 v[198:201], v[68:71], v[72:75], v[198:201]
	s_waitcnt lgkmcnt(5)
	v_mfma_f32_16x16x32_f16 v[142:145], v[76:79], v[64:67], v[142:145]
	v_mfma_f32_16x16x32_f16 v[158:161], v[76:79], v[72:75], v[158:161]
	s_waitcnt lgkmcnt(4)
	v_mfma_f32_16x16x32_f16 v[166:169], v[68:71], v[80:83], v[166:169]
	v_and_b32_e32 v10, 7, v148
	v_bfe_u32 v11, v148, 4, 3
	v_xor_b32_e32 v11, v11, v10
	v_sub_u32_e32 v11, v11, v10
	v_lshlrev_b32_e32 v10, 4, v11
	v_add_u32_e32 v10, 0x580, v10
	v_ashrrev_i32_e32 v11, 31, v10
	v_lshl_add_u64 v[28:29], v[108:109], 0, v[10:11]
	s_mov_b32 m0, s61
	s_nop 0
	global_load_lds_dwordx4 v[28:29], off
	s_waitcnt lgkmcnt(2)
	v_mfma_f32_16x16x32_f16 v[68:71], v[68:71], v[88:91], v[202:205]
	s_nop 2
	ds_read_b128 v[202:205], v135 offset:32768
	v_lshl_add_u64 v[24:25], v[110:111], 0, v[10:11]
	s_mov_b32 m0, s69
	s_nop 0
	global_load_lds_dwordx4 v[24:25], off
	v_mfma_f32_16x16x32_f16 v[190:193], v[76:79], v[80:83], v[190:193]
	v_lshl_add_u64 v[12:13], v[112:113], 0, v[10:11]
	s_mov_b32 m0, s73
	s_nop 0
	global_load_lds_dwordx4 v[12:13], off
	v_lshl_add_u64 v[16:17], v[114:115], 0, v[10:11]
	s_mov_b32 m0, s65
	s_nop 0
	global_load_lds_dwordx4 v[16:17], off
	v_mfma_f32_16x16x32_f16 v[76:79], v[76:79], v[88:91], v[210:213]
	s_nop 2
	ds_read_b128 v[210:213], v135 offset:34816
	v_mfma_f32_16x16x32_f16 v[154:157], v[84:87], v[64:67], v[154:157]
	v_lshl_add_u64 v[20:21], v[116:117], 0, v[10:11]
	s_mov_b32 m0, s63
	s_nop 0
	global_load_lds_dwordx4 v[20:21], off
	v_mfma_f32_16x16x32_f16 v[162:165], v[84:87], v[72:75], v[162:165]
	v_lshl_add_u64 v[0:1], v[118:119], 0, v[10:11]
	s_mov_b32 m0, s71
	s_nop 0
	global_load_lds_dwordx4 v[0:1], off
	s_waitcnt lgkmcnt(3)
	v_mfma_f32_16x16x32_f16 v[64:67], v[92:95], v[64:67], v[236:239]
	v_lshl_add_u64 v[4:5], v[120:121], 0, v[10:11]
	s_mov_b32 m0, s75
	s_nop 0
	global_load_lds_dwordx4 v[4:5], off
	v_mfma_f32_16x16x32_f16 v[72:75], v[92:95], v[72:75], v[206:209]
	s_nop 2
	ds_read_b128 v[206:209], v134 offset:2048
	v_mfma_f32_16x16x32_f16 v[194:197], v[84:87], v[80:83], v[194:197]
	v_lshl_add_u64 v[8:9], v[122:123], 0, v[10:11]
	s_mov_b32 m0, s67
	s_nop 0
	global_load_lds_dwordx4 v[8:9], off
	v_mfma_f32_16x16x32_f16 v[84:87], v[84:87], v[88:91], v[224:227]
	s_nop 2
	ds_read_b128 v[224:227], v135 offset:36864
	v_mfma_f32_16x16x32_f16 v[80:83], v[92:95], v[80:83], v[220:223]
	s_nop 2
	ds_read_b128 v[220:223], v134 offset:4096
	v_mfma_f32_16x16x32_f16 v[88:91], v[92:95], v[88:91], v[228:231]
	ds_read_b128 v[92:95], v134
	s_nop 1
	ds_read_b128 v[228:231], v134 offset:6144
	s_waitcnt vmcnt(0) lgkmcnt(0)
	s_barrier
	v_mfma_f32_16x16x32_f16 v[138:141], v[202:205], v[92:95], v[138:141]
	v_mfma_f32_16x16x32_f16 v[142:145], v[210:213], v[92:95], v[142:145]
	v_mfma_f32_16x16x32_f16 v[154:157], v[224:227], v[92:95], v[154:157]
	v_mfma_f32_16x16x32_f16 v[64:67], v[232:235], v[92:95], v[64:67]
	v_mfma_f32_16x16x32_f16 v[92:95], v[202:205], v[206:209], v[198:201]
	s_nop 2
	ds_read_b128 v[198:201], v133 offset:16384
	v_mfma_f32_16x16x32_f16 v[158:161], v[210:213], v[206:209], v[158:161]
	v_mfma_f32_16x16x32_f16 v[166:169], v[202:205], v[220:223], v[166:169]
	v_mfma_f32_16x16x32_f16 v[68:71], v[202:205], v[228:231], v[68:71]
	ds_read_b128 v[202:205], v136 offset:49152
	v_mfma_f32_16x16x32_f16 v[190:193], v[210:213], v[220:223], v[190:193]
	v_mfma_f32_16x16x32_f16 v[76:79], v[210:213], v[228:231], v[76:79]
	ds_read_b128 v[210:213], v136 offset:51200
	v_mfma_f32_16x16x32_f16 v[162:165], v[224:227], v[206:209], v[162:165]
	v_mfma_f32_16x16x32_f16 v[72:75], v[232:235], v[206:209], v[72:75]
	ds_read_b128 v[206:209], v133 offset:18432
	v_mfma_f32_16x16x32_f16 v[194:197], v[224:227], v[220:223], v[194:197]
	v_and_b32_e32 v38, 7, v148
	v_bfe_u32 v39, v148, 4, 3
	v_xor_b32_e32 v39, v39, v38
	v_sub_u32_e32 v39, v39, v38
	v_lshlrev_b32_e32 v38, 4, v39
	v_add_u32_e32 v38, 0x600, v38
	v_ashrrev_i32_e32 v39, 31, v38
	v_mfma_f32_16x16x32_f16 v[84:87], v[224:227], v[228:231], v[84:87]
	ds_read_b128 v[224:227], v136 offset:53248
	v_mfma_f32_16x16x32_f16 v[80:83], v[232:235], v[220:223], v[80:83]
	ds_read_b128 v[220:223], v133 offset:20480
	v_mfma_f32_16x16x32_f16 v[88:91], v[232:235], v[228:231], v[88:91]
	ds_read_b128 v[228:231], v133 offset:22528
	s_waitcnt lgkmcnt(5)
; #define GL_LOAD(s_, kt_) if (VAR != 1) { a##s_##0 = GL_A(0, kt_); a##s_##1 = GL_A(1, kt_); a##s_##2 = GL_A(2, kt_); a##s_##3 = GL_A(3, kt_); b##s_##0 = GL_B(0, kt_); b##s_##1 = GL_B(1, kt_); b##s_##2 = GL_B(2, kt_); b##s_##3 = GL_B(3, kt_); }
; #define LDS_STORE(s_, buf_) if (VAR != 2) { LDS_ST1(sA, 0, buf_, a##s_##0) LDS_ST1(sA, 1, buf_, a##s_##1) LDS_ST1(sA, 2, buf_, a##s_##2) LDS_ST1(sA, 3, buf_, a##s_##3) LDS_ST1(sB, 0, buf_, b##s_##0) LDS_ST1(sB, 1, buf_, b##s_##1) LDS_ST1(sB, 2, buf_, b##s_##2) LDS_ST1(sB, 3, buf_, b##s_##3) }
;     ...
;   GL_LOAD(0, 0)
;   GL_LOAD(1, 1)
;   LDS_STORE(0, 0)
;   if (VAR != 4) __syncthreads();
; #pragma unroll
;   for (int kt = 0; kt < nk; kt += 2) {
;     if (kt + 2 < nk) { GL_LOAD(0, kt + 2) }
;     MMA_TILE(0)
;     LDS_STORE(1, 1)
;     if (VAR != 4) __syncthreads();
;     if (kt + 3 < nk) { GL_LOAD(1, kt + 3) }
;     MMA_TILE(1)
;     if (kt + 2 < nk) { LDS_STORE(0, 0) }
;     if (VAR != 4) __syncthreads();
	v_mfma_f32_16x16x32_f16 v[138:141], v[202:205], v[198:201], v[138:141]
	ds_read_b128 v[232:235], v136 offset:55296
	s_waitcnt lgkmcnt(4)
	v_mfma_f32_16x16x32_f16 v[92:95], v[202:205], v[206:209], v[92:95]
	v_lshl_add_u64 v[52:53], v[108:109], 0, v[38:39]
	s_mov_b32 m0, s60
	s_nop 0
	global_load_lds_dwordx4 v[52:53], off
	v_mfma_f32_16x16x32_f16 v[142:145], v[210:213], v[198:201], v[142:145]
	v_lshl_add_u64 v[56:57], v[110:111], 0, v[38:39]
	s_mov_b32 m0, s68
	s_nop 0
	global_load_lds_dwordx4 v[56:57], off
	v_mfma_f32_16x16x32_f16 v[158:161], v[210:213], v[206:209], v[158:161]
	v_lshl_add_u64 v[60:61], v[112:113], 0, v[38:39]
	s_mov_b32 m0, s72
	s_nop 0
	global_load_lds_dwordx4 v[60:61], off
	s_waitcnt lgkmcnt(2)
	v_mfma_f32_16x16x32_f16 v[166:169], v[202:205], v[220:223], v[166:169]
	v_lshl_add_u64 v[40:41], v[114:115], 0, v[38:39]
	s_mov_b32 m0, s64
	s_nop 0
	global_load_lds_dwordx4 v[40:41], off
	s_waitcnt lgkmcnt(1)
	v_mfma_f32_16x16x32_f16 v[68:71], v[202:205], v[228:231], v[68:71]
	ds_read_b128 v[202:205], v135 offset:49152
	v_mfma_f32_16x16x32_f16 v[190:193], v[210:213], v[220:223], v[190:193]
	v_lshl_add_u64 v[44:45], v[116:117], 0, v[38:39]
	s_mov_b32 m0, s62
	s_nop 0
	global_load_lds_dwordx4 v[44:45], off
	v_mfma_f32_16x16x32_f16 v[76:79], v[210:213], v[228:231], v[76:79]
	ds_read_b128 v[210:213], v135 offset:51200
	v_mfma_f32_16x16x32_f16 v[154:157], v[224:227], v[198:201], v[154:157]
	v_lshl_add_u64 v[48:49], v[118:119], 0, v[38:39]
	s_mov_b32 m0, s70
	s_nop 0
	global_load_lds_dwordx4 v[48:49], off
	v_mfma_f32_16x16x32_f16 v[162:165], v[224:227], v[206:209], v[162:165]
	v_lshl_add_u64 v[32:33], v[120:121], 0, v[38:39]
	s_mov_b32 m0, s74
	s_nop 0
	global_load_lds_dwordx4 v[32:33], off
	s_waitcnt lgkmcnt(2)
	v_mfma_f32_16x16x32_f16 v[64:67], v[232:235], v[198:201], v[64:67]
	ds_read_b128 v[198:201], v134 offset:16384
	v_mfma_f32_16x16x32_f16 v[72:75], v[232:235], v[206:209], v[72:75]
	ds_read_b128 v[206:209], v134 offset:18432
	v_mfma_f32_16x16x32_f16 v[194:197], v[224:227], v[220:223], v[194:197]
	v_lshl_add_u64 v[36:37], v[122:123], 0, v[38:39]
	s_mov_b32 m0, s66
	s_nop 0
	global_load_lds_dwordx4 v[36:37], off
	v_mfma_f32_16x16x32_f16 v[84:87], v[224:227], v[228:231], v[84:87]
	ds_read_b128 v[224:227], v135 offset:53248
	v_mfma_f32_16x16x32_f16 v[80:83], v[232:235], v[220:223], v[80:83]
	ds_read_b128 v[220:223], v134 offset:20480
	v_mfma_f32_16x16x32_f16 v[88:91], v[232:235], v[228:231], v[88:91]
	ds_read_b128 v[228:231], v134 offset:22528
	ds_read_b128 v[232:235], v135 offset:55296
	s_waitcnt vmcnt(0) lgkmcnt(0)
	s_barrier
	v_mfma_f32_16x16x32_f16 v[138:141], v[202:205], v[198:201], v[138:141]
	v_and_b32_e32 v6, 7, v148
	v_bfe_u32 v7, v148, 4, 3
	v_xor_b32_e32 v7, v7, v6
	v_sub_u32_e32 v7, v7, v6
	v_lshlrev_b32_e32 v6, 4, v7
	v_add_u32_e32 v6, 0x680, v6
	v_ashrrev_i32_e32 v7, 31, v6
	v_mfma_f32_16x16x32_f16 v[92:95], v[202:205], v[206:209], v[92:95]
	global_load_dwordx4 v[60:63], v[108:109], off offset:1792
	v_mfma_f32_16x16x32_f16 v[142:145], v[210:213], v[198:201], v[142:145]
	global_load_dwordx4 v[48:51], v[110:111], off offset:1792
	v_mfma_f32_16x16x32_f16 v[158:161], v[210:213], v[206:209], v[158:161]
	global_load_dwordx4 v[52:55], v[112:113], off offset:1792
	v_mfma_f32_16x16x32_f16 v[166:169], v[202:205], v[220:223], v[166:169]
	global_load_dwordx4 v[56:59], v[114:115], off offset:1792
	v_mfma_f32_16x16x32_f16 v[68:71], v[202:205], v[228:231], v[68:71]
	ds_read_b128 v[202:205], v136 offset:32768
	v_mfma_f32_16x16x32_f16 v[190:193], v[210:213], v[220:223], v[190:193]
	global_load_dwordx4 v[36:39], v[116:117], off offset:1792
	v_mfma_f32_16x16x32_f16 v[76:79], v[210:213], v[228:231], v[76:79]
	ds_read_b128 v[210:213], v136 offset:34816
	v_mfma_f32_16x16x32_f16 v[154:157], v[224:227], v[198:201], v[154:157]
	global_load_dwordx4 v[40:43], v[118:119], off offset:1792
	v_mfma_f32_16x16x32_f16 v[162:165], v[224:227], v[206:209], v[162:165]
	global_load_dwordx4 v[44:47], v[120:121], off offset:1792
	v_mfma_f32_16x16x32_f16 v[64:67], v[232:235], v[198:201], v[64:67]
	ds_read_b128 v[198:201], v133
	v_mfma_f32_16x16x32_f16 v[72:75], v[232:235], v[206:209], v[72:75]
	ds_read_b128 v[206:209], v133 offset:2048
	v_mfma_f32_16x16x32_f16 v[194:197], v[224:227], v[220:223], v[194:197]
	global_load_dwordx4 v[32:35], v[122:123], off offset:1792
	v_mfma_f32_16x16x32_f16 v[84:87], v[224:227], v[228:231], v[84:87]
	ds_read_b128 v[224:227], v136 offset:36864
	v_mfma_f32_16x16x32_f16 v[80:83], v[232:235], v[220:223], v[80:83]
	ds_read_b128 v[220:223], v133 offset:4096
	v_mfma_f32_16x16x32_f16 v[88:91], v[232:235], v[228:231], v[88:91]
	ds_read_b128 v[228:231], v133 offset:6144
	s_waitcnt lgkmcnt(4)
	v_mfma_f32_16x16x32_f16 v[138:141], v[202:205], v[198:201], v[138:141]
	ds_read_b128 v[232:235], v136 offset:38912
	s_waitcnt lgkmcnt(4)
	v_mfma_f32_16x16x32_f16 v[92:95], v[202:205], v[206:209], v[92:95]
	v_lshl_add_u64 v[20:21], v[108:109], 0, v[6:7]
	s_mov_b32 m0, s61
	s_nop 0
	global_load_lds_dwordx4 v[20:21], off
	v_mfma_f32_16x16x32_f16 v[142:145], v[210:213], v[198:201], v[142:145]
	v_lshl_add_u64 v[24:25], v[110:111], 0, v[6:7]
	s_mov_b32 m0, s69
	s_nop 0
	global_load_lds_dwordx4 v[24:25], off
	v_mfma_f32_16x16x32_f16 v[158:161], v[210:213], v[206:209], v[158:161]
	v_lshl_add_u64 v[28:29], v[112:113], 0, v[6:7]
	s_mov_b32 m0, s73
	s_nop 0
	global_load_lds_dwordx4 v[28:29], off
	s_waitcnt lgkmcnt(2)
	v_mfma_f32_16x16x32_f16 v[166:169], v[202:205], v[220:223], v[166:169]
	v_lshl_add_u64 v[8:9], v[114:115], 0, v[6:7]
	s_mov_b32 m0, s65
	s_nop 0
	global_load_lds_dwordx4 v[8:9], off
	s_waitcnt lgkmcnt(1)
; #define GL_LOAD(s_, kt_) if (VAR != 1) { a##s_##0 = GL_A(0, kt_); a##s_##1 = GL_A(1, kt_); a##s_##2 = GL_A(2, kt_); a##s_##3 = GL_A(3, kt_); b##s_##0 = GL_B(0, kt_); b##s_##1 = GL_B(1, kt_); b##s_##2 = GL_B(2, kt_); b##s_##3 = GL_B(3, kt_); }
; #define LDS_STORE(s_, buf_) if (VAR != 2) { LDS_ST1(sA, 0, buf_, a##s_##0) LDS_ST1(sA, 1, buf_, a##s_##1) LDS_ST1(sA, 2, buf_, a##s_##2) LDS_ST1(sA, 3, buf_, a##s_##3) LDS_ST1(sB, 0, buf_, b##s_##0) LDS_ST1(sB, 1, buf_, b##s_##1) LDS_ST1(sB, 2, buf_, b##s_##2) LDS_ST1(sB, 3, buf_, b##s_##3) }
;     ...
;   GL_LOAD(0, 0)
;   GL_LOAD(1, 1)
;   LDS_STORE(0, 0)
;   if (VAR != 4) __syncthreads();
; #pragma unroll
;   for (int kt = 0; kt < nk; kt += 2) {
;     if (kt + 2 < nk) { GL_LOAD(0, kt + 2) }
;     MMA_TILE(0)
;     LDS_STORE(1, 1)
;     if (VAR != 4) __syncthreads();
;     if (kt + 3 < nk) { GL_LOAD(1, kt + 3) }
;     MMA_TILE(1)
;     if (kt + 2 < nk) { LDS_STORE(0, 0) }
;     if (VAR != 4) __syncthreads();
	v_mfma_f32_16x16x32_f16 v[68:71], v[202:205], v[228:231], v[68:71]
	ds_read_b128 v[202:205], v135 offset:32768
	v_mfma_f32_16x16x32_f16 v[190:193], v[210:213], v[220:223], v[190:193]
	v_lshl_add_u64 v[12:13], v[116:117], 0, v[6:7]
	s_mov_b32 m0, s63
	s_nop 0
	global_load_lds_dwordx4 v[12:13], off
	v_mfma_f32_16x16x32_f16 v[76:79], v[210:213], v[228:231], v[76:79]
	ds_read_b128 v[210:213], v135 offset:34816
	v_mfma_f32_16x16x32_f16 v[154:157], v[224:227], v[198:201], v[154:157]
	v_lshl_add_u64 v[16:17], v[118:119], 0, v[6:7]
	s_mov_b32 m0, s71
	s_nop 0
	global_load_lds_dwordx4 v[16:17], off
	v_mfma_f32_16x16x32_f16 v[162:165], v[224:227], v[206:209], v[162:165]
	v_lshl_add_u64 v[0:1], v[120:121], 0, v[6:7]
	s_mov_b32 m0, s75
	s_nop 0
	global_load_lds_dwordx4 v[0:1], off
	s_waitcnt lgkmcnt(2)
	v_mfma_f32_16x16x32_f16 v[64:67], v[232:235], v[198:201], v[64:67]
	ds_read_b128 v[198:201], v134
	v_mfma_f32_16x16x32_f16 v[72:75], v[232:235], v[206:209], v[72:75]
	ds_read_b128 v[206:209], v134 offset:2048
	v_mfma_f32_16x16x32_f16 v[194:197], v[224:227], v[220:223], v[194:197]
	v_lshl_add_u64 v[4:5], v[122:123], 0, v[6:7]
	s_mov_b32 m0, s67
	s_nop 0
	global_load_lds_dwordx4 v[4:5], off
	v_mfma_f32_16x16x32_f16 v[84:87], v[224:227], v[228:231], v[84:87]
	ds_read_b128 v[224:227], v135 offset:36864
	v_mfma_f32_16x16x32_f16 v[80:83], v[232:235], v[220:223], v[80:83]
	ds_read_b128 v[220:223], v134 offset:4096
	v_mfma_f32_16x16x32_f16 v[88:91], v[232:235], v[228:231], v[88:91]
	ds_read_b128 v[228:231], v134 offset:6144
	ds_read_b128 v[232:235], v135 offset:38912
	s_waitcnt vmcnt(0) lgkmcnt(0)
	s_barrier
	v_mfma_f32_16x16x32_f16 v[138:141], v[202:205], v[198:201], v[138:141]
	global_load_dwordx4 v[28:31], v[108:109], off offset:1920
	v_mfma_f32_16x16x32_f16 v[92:95], v[202:205], v[206:209], v[92:95]
	global_load_dwordx4 v[16:19], v[110:111], off offset:1920
	v_mfma_f32_16x16x32_f16 v[142:145], v[210:213], v[198:201], v[142:145]
	ds_read_b128 v[108:111], v133 offset:16384
	v_mfma_f32_16x16x32_f16 v[158:161], v[210:213], v[206:209], v[158:161]
	global_load_dwordx4 v[20:23], v[112:113], off offset:1920
	v_mfma_f32_16x16x32_f16 v[166:169], v[202:205], v[220:223], v[166:169]
	global_load_dwordx4 v[24:27], v[114:115], off offset:1920
	v_mfma_f32_16x16x32_f16 v[68:71], v[202:205], v[228:231], v[68:71]
	ds_read_b128 v[112:115], v136 offset:49152
	v_mfma_f32_16x16x32_f16 v[190:193], v[210:213], v[220:223], v[190:193]
	ds_read_b128 v[202:205], v136 offset:53248
	v_mfma_f32_16x16x32_f16 v[76:79], v[210:213], v[228:231], v[76:79]
	ds_read_b128 v[210:213], v136 offset:55296
	v_mfma_f32_16x16x32_f16 v[154:157], v[224:227], v[198:201], v[154:157]
	global_load_dwordx4 v[4:7], v[116:117], off offset:1920
	v_mfma_f32_16x16x32_f16 v[162:165], v[224:227], v[206:209], v[162:165]
	global_load_dwordx4 v[8:11], v[118:119], off offset:1920
	v_mfma_f32_16x16x32_f16 v[64:67], v[232:235], v[198:201], v[64:67]
	ds_read_b128 v[116:119], v133 offset:18432
	v_mfma_f32_16x16x32_f16 v[72:75], v[232:235], v[206:209], v[72:75]
	ds_read_b128 v[198:201], v133 offset:20480
	v_mfma_f32_16x16x32_f16 v[194:197], v[224:227], v[220:223], v[194:197]
	ds_read_b128 v[206:209], v133 offset:22528
	v_mfma_f32_16x16x32_f16 v[84:87], v[224:227], v[228:231], v[84:87]
	global_load_dwordx4 v[12:15], v[120:121], off offset:1920
	v_mfma_f32_16x16x32_f16 v[80:83], v[232:235], v[220:223], v[80:83]
	global_load_dwordx4 v[0:3], v[122:123], off offset:1920
	v_mfma_f32_16x16x32_f16 v[88:91], v[232:235], v[228:231], v[88:91]
	ds_read_b128 v[120:123], v136 offset:51200
	s_waitcnt lgkmcnt(6)
	v_mfma_f32_16x16x32_f16 v[138:141], v[112:115], v[108:111], v[138:141]
	ds_write_b128 v101, v[60:63]
	s_waitcnt lgkmcnt(4)
	v_mfma_f32_16x16x32_f16 v[92:95], v[112:115], v[116:119], v[92:95]
	ds_write_b128 v131, v[48:51]
	s_waitcnt lgkmcnt(2)
	v_mfma_f32_16x16x32_f16 v[142:145], v[120:123], v[108:111], v[142:145]
	ds_write_b128 v132, v[52:55]
	v_mfma_f32_16x16x32_f16 v[154:157], v[202:205], v[108:111], v[154:157]
	v_mfma_f32_16x16x32_f16 v[64:67], v[210:213], v[108:111], v[64:67]
	v_mfma_f32_16x16x32_f16 v[108:111], v[120:123], v[116:119], v[158:161]
	ds_write_b128 v130, v[56:59]
	v_mfma_f32_16x16x32_f16 v[158:161], v[202:205], v[116:119], v[162:165]
	v_mfma_f32_16x16x32_f16 v[72:75], v[210:213], v[116:119], v[72:75]
	v_mfma_f32_16x16x32_f16 v[116:119], v[112:115], v[198:201], v[166:169]
	ds_write_b128 v101, v[36:39] offset:32768
	ds_write_b128 v131, v[40:43] offset:32768
	v_mfma_f32_16x16x32_f16 v[68:71], v[112:115], v[206:209], v[68:71]
	ds_read_b128 v[112:115], v134 offset:16384
	ds_write_b128 v132, v[44:47] offset:32768
	v_mfma_f32_16x16x32_f16 v[162:165], v[120:123], v[198:201], v[190:193]
	s_nop 2
	ds_read_b128 v[190:193], v134 offset:18432
	v_mfma_f32_16x16x32_f16 v[76:79], v[120:123], v[206:209], v[76:79]
	ds_read_b128 v[120:123], v135 offset:49152
	ds_write_b128 v130, v[32:35] offset:32768
	v_mfma_f32_16x16x32_f16 v[166:169], v[202:205], v[198:201], v[194:197]
	s_nop 2
	ds_read_b128 v[194:197], v135 offset:51200
	v_mfma_f32_16x16x32_f16 v[84:87], v[202:205], v[206:209], v[84:87]
	ds_read_b128 v[202:205], v135 offset:53248
	v_mfma_f32_16x16x32_f16 v[80:83], v[210:213], v[198:201], v[80:83]
	ds_read_b128 v[198:201], v134 offset:20480
	v_mfma_f32_16x16x32_f16 v[88:91], v[210:213], v[206:209], v[88:91]
	ds_read_b128 v[206:209], v134 offset:22528
	s_waitcnt lgkmcnt(5)
	v_mfma_f32_16x16x32_f16 v[138:141], v[120:123], v[112:115], v[138:141]
	ds_read_b128 v[210:213], v135 offset:55296
	s_waitcnt lgkmcnt(0)
	s_barrier
; #define GL_LOAD(s_, kt_) if (VAR != 1) { a##s_##0 = GL_A(0, kt_); a##s_##1 = GL_A(1, kt_); a##s_##2 = GL_A(2, kt_); a##s_##3 = GL_A(3, kt_); b##s_##0 = GL_B(0, kt_); b##s_##1 = GL_B(1, kt_); b##s_##2 = GL_B(2, kt_); b##s_##3 = GL_B(3, kt_); }
; #define LDS_STORE(s_, buf_) if (VAR != 2) { LDS_ST1(sA, 0, buf_, a##s_##0) LDS_ST1(sA, 1, buf_, a##s_##1) LDS_ST1(sA, 2, buf_, a##s_##2) LDS_ST1(sA, 3, buf_, a##s_##3) LDS_ST1(sB, 0, buf_, b##s_##0) LDS_ST1(sB, 1, buf_, b##s_##1) LDS_ST1(sB, 2, buf_, b##s_##2) LDS_ST1(sB, 3, buf_, b##s_##3) }
;     ...
;   GL_LOAD(0, 0)
;   GL_LOAD(1, 1)
;   LDS_STORE(0, 0)
;   if (VAR != 4) __syncthreads();
; #pragma unroll
;   for (int kt = 0; kt < nk; kt += 2) {
;     if (kt + 2 < nk) { GL_LOAD(0, kt + 2) }
;     MMA_TILE(0)
;     LDS_STORE(1, 1)
;     if (VAR != 4) __syncthreads();
;     if (kt + 3 < nk) { GL_LOAD(1, kt + 3) }
;     MMA_TILE(1)
;     if (kt + 2 < nk) { LDS_STORE(0, 0) }
;     if (VAR != 4) __syncthreads();
	v_mfma_f32_16x16x32_f16 v[142:145], v[194:197], v[112:115], v[142:145]
	ds_read_b128 v[32:35], v133
	v_mfma_f32_16x16x32_f16 v[108:111], v[194:197], v[190:193], v[108:111]
	ds_read_b128 v[36:39], v136 offset:32768
	v_mfma_f32_16x16x32_f16 v[154:157], v[202:205], v[112:115], v[154:157]
	ds_read_b128 v[40:43], v133 offset:2048
	v_mfma_f32_16x16x32_f16 v[64:67], v[210:213], v[112:115], v[64:67]
	v_mfma_f32_16x16x32_f16 v[112:115], v[202:205], v[190:193], v[158:161]
	ds_read_b128 v[44:47], v136 offset:34816
	v_mfma_f32_16x16x32_f16 v[158:161], v[194:197], v[198:201], v[162:165]
	ds_read_b128 v[48:51], v133 offset:4096
	v_mfma_f32_16x16x32_f16 v[76:79], v[194:197], v[206:209], v[76:79]
	ds_read_b128 v[52:55], v136 offset:36864
	v_mfma_f32_16x16x32_f16 v[162:165], v[202:205], v[198:201], v[166:169]
	ds_read_b128 v[56:59], v133 offset:6144
	v_mfma_f32_16x16x32_f16 v[84:87], v[202:205], v[206:209], v[84:87]
	ds_read_b128 v[60:63], v136 offset:38912
	s_waitcnt vmcnt(7)
	ds_write_b128 v101, v[28:31] offset:16384
	v_mfma_f32_16x16x32_f16 v[72:75], v[210:213], v[190:193], v[72:75]
	s_waitcnt vmcnt(6)
	ds_write_b128 v131, v[16:19] offset:16384
	v_mfma_f32_16x16x32_f16 v[92:95], v[120:123], v[190:193], v[92:95]
	s_waitcnt vmcnt(5)
	ds_write_b128 v132, v[20:23] offset:16384
	v_mfma_f32_16x16x32_f16 v[80:83], v[210:213], v[198:201], v[80:83]
	s_waitcnt vmcnt(4)
	ds_write_b128 v130, v[24:27] offset:16384
	v_mfma_f32_16x16x32_f16 v[88:91], v[210:213], v[206:209], v[88:91]
	s_waitcnt vmcnt(3)
	ds_write_b128 v101, v[4:7] offset:49152
	v_mfma_f32_16x16x32_f16 v[116:119], v[120:123], v[198:201], v[116:119]
	s_waitcnt vmcnt(2)
	ds_write_b128 v131, v[8:11] offset:49152
	v_mfma_f32_16x16x32_f16 v[68:71], v[120:123], v[206:209], v[68:71]
	s_waitcnt vmcnt(1)
	ds_write_b128 v132, v[12:15] offset:49152
	s_waitcnt lgkmcnt(13)
	v_mfma_f32_16x16x32_f16 v[120:123], v[36:39], v[32:35], v[138:141]
	s_waitcnt vmcnt(0)
	ds_write_b128 v130, v[0:3] offset:49152
	s_waitcnt lgkmcnt(12)
	v_mfma_f32_16x16x32_f16 v[138:141], v[44:47], v[32:35], v[142:145]
	s_waitcnt lgkmcnt(10)
	v_mfma_f32_16x16x32_f16 v[142:145], v[52:55], v[32:35], v[154:157]
	s_waitcnt lgkmcnt(8)
	v_mfma_f32_16x16x32_f16 v[32:35], v[60:63], v[32:35], v[64:67]
	v_mfma_f32_16x16x32_f16 v[64:67], v[36:39], v[40:43], v[92:95]
	ds_read_b128 v[154:157], v134 offset:6144
	v_mfma_f32_16x16x32_f16 v[92:95], v[44:47], v[40:43], v[108:111]
	v_mfma_f32_16x16x32_f16 v[108:111], v[52:55], v[40:43], v[112:115]
	v_mfma_f32_16x16x32_f16 v[40:43], v[60:63], v[40:43], v[72:75]
	v_mfma_f32_16x16x32_f16 v[72:75], v[36:39], v[48:51], v[116:119]
	v_mfma_f32_16x16x32_f16 v[36:39], v[36:39], v[56:59], v[68:71]
	s_nop 2
	ds_read_b128 v[68:71], v135 offset:32768
	v_mfma_f32_16x16x32_f16 v[112:115], v[44:47], v[48:51], v[158:161]
	s_nop 2
	ds_read_b128 v[158:161], v135 offset:38912
	v_mfma_f32_16x16x32_f16 v[44:47], v[44:47], v[56:59], v[76:79]
	s_nop 2
	ds_read_b128 v[76:79], v134 offset:2048
	v_mfma_f32_16x16x32_f16 v[116:119], v[52:55], v[48:51], v[162:165]
	v_mfma_f32_16x16x32_f16 v[52:55], v[52:55], v[56:59], v[84:87]
	s_nop 2
	ds_read_b128 v[84:87], v134 offset:4096
	v_mfma_f32_16x16x32_f16 v[48:51], v[60:63], v[48:51], v[80:83]
	s_nop 2
	ds_read_b128 v[80:83], v135 offset:34816
	v_mfma_f32_16x16x32_f16 v[56:59], v[60:63], v[56:59], v[88:91]
	ds_read_b128 v[60:63], v134
	s_waitcnt lgkmcnt(0)
	v_mfma_f32_16x16x32_f16 v[120:123], v[68:71], v[60:63], v[120:123]
	ds_read_b128 v[88:91], v135 offset:36864
	s_waitcnt lgkmcnt(0)
	s_barrier
	v_mfma_f32_16x16x32_f16 v[138:141], v[80:83], v[60:63], v[138:141]
	ds_read_b128 v[0:3], v133 offset:16384
	v_mfma_f32_16x16x32_f16 v[142:145], v[88:91], v[60:63], v[142:145]
	v_mfma_f32_16x16x32_f16 v[32:35], v[158:161], v[60:63], v[32:35]
	v_mfma_f32_16x16x32_f16 v[60:63], v[68:71], v[76:79], v[64:67]
	v_mfma_f32_16x16x32_f16 v[64:67], v[80:83], v[76:79], v[92:95]
	ds_read_b128 v[4:7], v136 offset:49152
	ds_read_b128 v[8:11], v133 offset:18432
	v_mfma_f32_16x16x32_f16 v[92:95], v[88:91], v[76:79], v[108:111]
	ds_read_b128 v[12:15], v136 offset:51200
	v_mfma_f32_16x16x32_f16 v[40:43], v[158:161], v[76:79], v[40:43]
	v_mfma_f32_16x16x32_f16 v[76:79], v[80:83], v[84:87], v[112:115]
	ds_read_b128 v[16:19], v133 offset:20480
	v_mfma_f32_16x16x32_f16 v[44:47], v[80:83], v[154:157], v[44:47]
	ds_read_b128 v[20:23], v136 offset:53248
	v_mfma_f32_16x16x32_f16 v[108:111], v[88:91], v[84:87], v[116:119]
	ds_read_b128 v[24:27], v133 offset:22528
	v_mfma_f32_16x16x32_f16 v[52:55], v[88:91], v[154:157], v[52:55]
	ds_read_b128 v[28:31], v136 offset:55296
	ds_read_b128 v[112:115], v135 offset:53248
	ds_read_b128 v[116:119], v134 offset:22528
	v_ashrrev_i32_e32 v101, 31, v100
	v_mfma_f32_16x16x32_f16 v[48:51], v[158:161], v[84:87], v[48:51]
	v_mfma_f32_16x16x32_f16 v[56:59], v[158:161], v[154:157], v[56:59]
	v_mfma_f32_16x16x32_f16 v[72:75], v[68:71], v[84:87], v[72:75]
	v_mfma_f32_16x16x32_f16 v[36:39], v[68:71], v[154:157], v[36:39]
	s_waitcnt lgkmcnt(8)
	v_mfma_f32_16x16x32_f16 v[68:71], v[4:7], v[0:3], v[120:123]
	s_nop 2
	ds_read_b128 v[120:123], v135 offset:55296
	s_waitcnt lgkmcnt(7)
	v_mfma_f32_16x16x32_f16 v[80:83], v[12:15], v[0:3], v[138:141]
	s_waitcnt lgkmcnt(5)
	v_mfma_f32_16x16x32_f16 v[84:87], v[20:23], v[0:3], v[142:145]
	s_waitcnt lgkmcnt(3)
	v_mfma_f32_16x16x32_f16 v[0:3], v[28:31], v[0:3], v[32:35]
	v_mfma_f32_16x16x32_f16 v[32:35], v[4:7], v[8:11], v[60:63]
	v_mfma_f32_16x16x32_f16 v[60:63], v[12:15], v[8:11], v[64:67]
	v_mfma_f32_16x16x32_f16 v[72:75], v[4:7], v[16:19], v[72:75]
	v_mfma_f32_16x16x32_f16 v[76:79], v[12:15], v[16:19], v[76:79]
	v_mfma_f32_16x16x32_f16 v[44:47], v[12:15], v[24:27], v[44:47]
	ds_read_b128 v[12:15], v134 offset:16384
	v_mfma_f32_16x16x32_f16 v[64:67], v[20:23], v[8:11], v[92:95]
	s_nop 2
	ds_read_b128 v[92:95], v135 offset:51200
	v_mfma_f32_16x16x32_f16 v[88:91], v[20:23], v[16:19], v[108:111]
	s_nop 2
	ds_read_b128 v[108:111], v134 offset:20480
	v_mfma_f32_16x16x32_f16 v[16:19], v[28:31], v[16:19], v[48:51]
	v_mfma_f32_16x16x32_f16 v[48:51], v[20:23], v[24:27], v[52:55]
	ds_read_b128 v[20:23], v134 offset:18432
	v_mfma_f32_16x16x32_f16 v[52:55], v[28:31], v[24:27], v[56:59]
	s_nop 2
	ds_read_b128 v[56:59], v135 offset:49152
	s_waitcnt lgkmcnt(0)
	s_barrier
; DI unsigned pack2(float lo, float hi) { f2_t v = {lo, hi}; h2_t b = __builtin_convertvector(v, h2_t); return __builtin_bit_cast(unsigned, b); }
; template <int VAR> DI void phase_up(const Params& P, int l, char* smem) {
;     ...
; #pragma unroll
;     for (int mt = 0; mt < 4; ++mt) {
;       const int row = row0 + mt * 16 + lr;
; #pragma unroll
;       for (int nt = 0; nt < 4; ++nt) {
;         float v[4];
; #pragma unroll
;         for (int j = 0; j < 4; ++j) { const float a = fmaxf(acc[mt][nt][j] * rs[mt], 0.f); v[j] = a * a; }
;         *(uint2*)(U + (size_t)row * DFF + col0 + nt * 16 + 4 * g) = make_uint2(pack2(v[0], v[1]), pack2(v[2], v[3]));
;       }
	s_setprio 0
	v_readlane_b32 s60, v255, 0
	v_readlane_b32 s61, v255, 1
	v_readlane_b32 s62, v255, 2
	v_readlane_b32 s63, v255, 3
	v_readlane_b32 s64, v255, 4
	v_readlane_b32 s65, v255, 5
	v_readlane_b32 s66, v255, 6
	v_readlane_b32 s67, v255, 7
	v_readlane_b32 s68, v255, 8
	v_readlane_b32 s69, v255, 9
	v_readlane_b32 s70, v255, 10
	v_readlane_b32 s71, v255, 11
	v_readlane_b32 s72, v255, 12
	v_readlane_b32 s73, v255, 13
	v_readlane_b32 s74, v255, 14
	v_readlane_b32 s75, v255, 15
	s_nop 4
	v_mfma_f32_16x16x32_f16 v[4:7], v[4:7], v[24:27], v[36:39]
	v_mfma_f32_16x16x32_f16 v[68:71], v[56:59], v[12:15], v[68:71]
	v_mfma_f32_16x16x32_f16 v[8:11], v[28:31], v[8:11], v[40:43]
	v_mfma_f32_16x16x32_f16 v[80:83], v[92:95], v[12:15], v[80:83]
	v_mfma_f32_16x16x32_f16 v[84:87], v[112:115], v[12:15], v[84:87]
	v_mfma_f32_16x16x32_f16 v[130:133], v[120:123], v[12:15], v[0:3]
	v_mfma_f32_16x16x32_f16 v[12:15], v[56:59], v[116:119], v[4:7]
	v_mfma_f32_16x16x32_f16 v[4:7], v[112:115], v[116:119], v[48:51]
	v_mfma_f32_16x16x32_f16 v[134:137], v[56:59], v[20:23], v[32:35]
	v_mfma_f32_16x16x32_f16 v[32:35], v[120:123], v[20:23], v[8:11]
	v_mfma_f32_16x16x32_f16 v[8:11], v[92:95], v[116:119], v[44:47]
	v_mfma_f32_16x16x32_f16 v[16:19], v[120:123], v[108:111], v[16:19]
	v_mfma_f32_16x16x32_f16 v[40:43], v[92:95], v[20:23], v[60:63]
	v_mfma_f32_16x16x32_f16 v[36:39], v[112:115], v[20:23], v[64:67]
	v_mfma_f32_16x16x32_f16 v[28:31], v[56:59], v[108:111], v[72:75]
	v_mfma_f32_16x16x32_f16 v[24:27], v[92:95], v[108:111], v[76:79]
	v_mfma_f32_16x16x32_f16 v[20:23], v[112:115], v[108:111], v[88:91]
	v_mfma_f32_16x16x32_f16 v[0:3], v[120:123], v[116:119], v[52:55]
	v_lshl_add_u64 v[44:45], v[100:101], 1, v[96:97]
	v_and_b32_e32 v250, 16, v148
	v_lshrrev_b32_e32 v251, 1, v250
	v_add_u32_e32 v250, v250, v251
	v_and_b32_e32 v251, 8, v148
	v_lshl_add_u32 v250, v251, 3, v250
	v_lshlrev_b32_e32 v251, 13, v251
	v_sub_u32_e32 v250, v250, v251
	v_ashrrev_i32_e32 v251, 31, v250
	v_lshl_add_u64 v[44:45], v[250:251], 0, v[44:45]
	v_mov_b32_e32 v248, 0x10000
	v_mov_b32_e32 v249, 0
	v_lshlrev_b64 v[46:47], 13, v[102:103]
	v_lshl_add_u64 v[46:47], v[44:45], 0, v[46:47]
	v_lshl_add_u64 v[48:49], v[248:249], 0, v[46:47]
	v_mul_f32_e32 v68, v128, v68
	v_mul_f32_e32 v69, v128, v69
	v_mul_f32_e32 v70, v128, v70
	v_mul_f32_e32 v71, v128, v71
	v_mul_f32_e32 v80, v128, v80
	v_mul_f32_e32 v81, v128, v81
	v_mul_f32_e32 v82, v128, v82
	v_mul_f32_e32 v83, v128, v83
	v_max_f32_e32 v68, 0, v68
	v_max_f32_e32 v69, 0, v69
	v_max_f32_e32 v70, 0, v70
	v_max_f32_e32 v71, 0, v71
	v_max_f32_e32 v80, 0, v80
	v_max_f32_e32 v81, 0, v81
	v_max_f32_e32 v82, 0, v82
	v_max_f32_e32 v83, 0, v83
	v_mul_f32_e32 v68, v68, v68
	v_mul_f32_e32 v69, v69, v69
	v_mul_f32_e32 v70, v70, v70
	v_mul_f32_e32 v71, v71, v71
	v_mul_f32_e32 v80, v80, v80
	v_mul_f32_e32 v81, v81, v81
	v_mul_f32_e32 v82, v82, v82
	v_mul_f32_e32 v83, v83, v83
	v_cvt_pk_f16_f32 v68, v68, v69
	v_cvt_pk_f16_f32 v69, v70, v71
	v_cvt_pk_f16_f32 v70, v80, v81
	v_cvt_pk_f16_f32 v71, v82, v83
	s_nop 1
	v_permlane16_swap_b32_e32 v68, v70
	v_permlane16_swap_b32_e32 v69, v71
	v_mul_f32_e32 v84, v128, v84
	v_mul_f32_e32 v85, v128, v85
	v_mul_f32_e32 v86, v128, v86
	v_mul_f32_e32 v87, v128, v87
	v_mul_f32_e32 v130, v128, v130
	v_mul_f32_e32 v131, v128, v131
	v_mul_f32_e32 v132, v128, v132
	v_mul_f32_e32 v133, v128, v133
	v_max_f32_e32 v84, 0, v84
	v_max_f32_e32 v85, 0, v85
	v_max_f32_e32 v86, 0, v86
	v_max_f32_e32 v87, 0, v87
	v_max_f32_e32 v130, 0, v130
	v_max_f32_e32 v131, 0, v131
	v_max_f32_e32 v132, 0, v132
	v_max_f32_e32 v133, 0, v133
	v_mul_f32_e32 v84, v84, v84
	v_mul_f32_e32 v85, v85, v85
	v_mul_f32_e32 v86, v86, v86
	v_mul_f32_e32 v87, v87, v87
	v_mul_f32_e32 v130, v130, v130
	v_mul_f32_e32 v131, v131, v131
	v_mul_f32_e32 v132, v132, v132
	v_mul_f32_e32 v133, v133, v133
	v_cvt_pk_f16_f32 v84, v84, v85
	v_cvt_pk_f16_f32 v85, v86, v87
	v_cvt_pk_f16_f32 v86, v130, v131
	v_cvt_pk_f16_f32 v87, v132, v133
	s_nop 1
	v_permlane16_swap_b32_e32 v84, v86
	v_permlane16_swap_b32_e32 v85, v87
	s_nop 1
	v_mov_b32_dpp v240, v68 row_ror:8 row_mask:0xf bank_mask:0x3
	v_mov_b32_dpp v241, v69 row_ror:8 row_mask:0xf bank_mask:0x3
	v_mov_b32_dpp v242, v70 row_ror:8 row_mask:0xf bank_mask:0x3
	v_mov_b32_dpp v243, v71 row_ror:8 row_mask:0xf bank_mask:0x3
	v_mov_b32_dpp v68, v84 row_ror:8 row_mask:0xf bank_mask:0xc
	v_mov_b32_dpp v69, v85 row_ror:8 row_mask:0xf bank_mask:0xc
	v_mov_b32_dpp v70, v86 row_ror:8 row_mask:0xf bank_mask:0xc
	v_mov_b32_dpp v71, v87 row_ror:8 row_mask:0xf bank_mask:0xc
	v_mov_b32_dpp v84, v240 quad_perm:[0,1,2,3] row_mask:0xf bank_mask:0x3
	v_mov_b32_dpp v85, v241 quad_perm:[0,1,2,3] row_mask:0xf bank_mask:0x3
	v_mov_b32_dpp v86, v242 quad_perm:[0,1,2,3] row_mask:0xf bank_mask:0x3
	v_mov_b32_dpp v87, v243 quad_perm:[0,1,2,3] row_mask:0xf bank_mask:0x3
	global_store_dwordx4 v[46:47], v[68:71], off
	global_store_dwordx4 v[48:49], v[84:87], off
	v_lshlrev_b64 v[46:47], 13, v[98:99]
	v_lshl_add_u64 v[46:47], v[44:45], 0, v[46:47]
	v_lshl_add_u64 v[48:49], v[248:249], 0, v[46:47]
	v_mul_f32_e32 v134, v126, v134
	v_mul_f32_e32 v135, v126, v135
	v_mul_f32_e32 v136, v126, v136
	v_mul_f32_e32 v137, v126, v137
	v_mul_f32_e32 v40, v126, v40
	v_mul_f32_e32 v41, v126, v41
	v_mul_f32_e32 v42, v126, v42
	v_mul_f32_e32 v43, v126, v43
	v_max_f32_e32 v134, 0, v134
	v_max_f32_e32 v135, 0, v135
	v_max_f32_e32 v136, 0, v136
	v_max_f32_e32 v137, 0, v137
	v_max_f32_e32 v40, 0, v40
	v_max_f32_e32 v41, 0, v41
	v_max_f32_e32 v42, 0, v42
	v_max_f32_e32 v43, 0, v43
	v_mul_f32_e32 v134, v134, v134
	v_mul_f32_e32 v135, v135, v135
	v_mul_f32_e32 v136, v136, v136
; DI unsigned pack2(float lo, float hi) { f2_t v = {lo, hi}; h2_t b = __builtin_convertvector(v, h2_t); return __builtin_bit_cast(unsigned, b); }
; template <int VAR> DI void phase_up(const Params& P, int l, char* smem) {
;     ...
; #pragma unroll
;     for (int mt = 0; mt < 4; ++mt) {
;       const int row = row0 + mt * 16 + lr;
; #pragma unroll
;       for (int nt = 0; nt < 4; ++nt) {
;         float v[4];
; #pragma unroll
;         for (int j = 0; j < 4; ++j) { const float a = fmaxf(acc[mt][nt][j] * rs[mt], 0.f); v[j] = a * a; }
;         *(uint2*)(U + (size_t)row * DFF + col0 + nt * 16 + 4 * g) = make_uint2(pack2(v[0], v[1]), pack2(v[2], v[3]));
;       }
	v_mul_f32_e32 v137, v137, v137
	v_mul_f32_e32 v40, v40, v40
	v_mul_f32_e32 v41, v41, v41
	v_mul_f32_e32 v42, v42, v42
	v_mul_f32_e32 v43, v43, v43
	v_cvt_pk_f16_f32 v244, v134, v135
	v_cvt_pk_f16_f32 v245, v136, v137
	v_cvt_pk_f16_f32 v246, v40, v41
	v_cvt_pk_f16_f32 v247, v42, v43
	s_nop 1
	v_permlane16_swap_b32_e32 v244, v246
	v_permlane16_swap_b32_e32 v245, v247
	v_mul_f32_e32 v36, v126, v36
	v_mul_f32_e32 v37, v126, v37
	v_mul_f32_e32 v38, v126, v38
	v_mul_f32_e32 v39, v126, v39
	v_mul_f32_e32 v32, v126, v32
	v_mul_f32_e32 v33, v126, v33
	v_mul_f32_e32 v34, v126, v34
	v_mul_f32_e32 v35, v126, v35
	v_max_f32_e32 v36, 0, v36
	v_max_f32_e32 v37, 0, v37
	v_max_f32_e32 v38, 0, v38
	v_max_f32_e32 v39, 0, v39
	v_max_f32_e32 v32, 0, v32
	v_max_f32_e32 v33, 0, v33
	v_max_f32_e32 v34, 0, v34
	v_max_f32_e32 v35, 0, v35
	v_mul_f32_e32 v36, v36, v36
	v_mul_f32_e32 v37, v37, v37
	v_mul_f32_e32 v38, v38, v38
	v_mul_f32_e32 v39, v39, v39
	v_mul_f32_e32 v32, v32, v32
	v_mul_f32_e32 v33, v33, v33
	v_mul_f32_e32 v34, v34, v34
	v_mul_f32_e32 v35, v35, v35
	v_cvt_pk_f16_f32 v36, v36, v37
	v_cvt_pk_f16_f32 v37, v38, v39
	v_cvt_pk_f16_f32 v38, v32, v33
	v_cvt_pk_f16_f32 v39, v34, v35
	s_nop 1
	v_permlane16_swap_b32_e32 v36, v38
	v_permlane16_swap_b32_e32 v37, v39
	s_nop 1
	v_mov_b32_dpp v240, v244 row_ror:8 row_mask:0xf bank_mask:0x3
	v_mov_b32_dpp v241, v245 row_ror:8 row_mask:0xf bank_mask:0x3
	v_mov_b32_dpp v242, v246 row_ror:8 row_mask:0xf bank_mask:0x3
	v_mov_b32_dpp v243, v247 row_ror:8 row_mask:0xf bank_mask:0x3
	v_mov_b32_dpp v244, v36 row_ror:8 row_mask:0xf bank_mask:0xc
	v_mov_b32_dpp v245, v37 row_ror:8 row_mask:0xf bank_mask:0xc
	v_mov_b32_dpp v246, v38 row_ror:8 row_mask:0xf bank_mask:0xc
	v_mov_b32_dpp v247, v39 row_ror:8 row_mask:0xf bank_mask:0xc
	v_mov_b32_dpp v36, v240 quad_perm:[0,1,2,3] row_mask:0xf bank_mask:0x3
	v_mov_b32_dpp v37, v241 quad_perm:[0,1,2,3] row_mask:0xf bank_mask:0x3
	v_mov_b32_dpp v38, v242 quad_perm:[0,1,2,3] row_mask:0xf bank_mask:0x3
	v_mov_b32_dpp v39, v243 quad_perm:[0,1,2,3] row_mask:0xf bank_mask:0x3
	global_store_dwordx4 v[46:47], v[244:247], off
	global_store_dwordx4 v[48:49], v[36:39], off
	v_lshlrev_b64 v[46:47], 13, v[106:107]
	v_lshl_add_u64 v[46:47], v[44:45], 0, v[46:47]
	v_lshl_add_u64 v[48:49], v[248:249], 0, v[46:47]
	v_mul_f32_e32 v28, v129, v28
	v_mul_f32_e32 v29, v129, v29
	v_mul_f32_e32 v30, v129, v30
	v_mul_f32_e32 v31, v129, v31
	v_mul_f32_e32 v24, v129, v24
	v_mul_f32_e32 v25, v129, v25
	v_mul_f32_e32 v26, v129, v26
	v_mul_f32_e32 v27, v129, v27
	v_max_f32_e32 v28, 0, v28
	v_max_f32_e32 v29, 0, v29
	v_max_f32_e32 v30, 0, v30
	v_max_f32_e32 v31, 0, v31
	v_max_f32_e32 v24, 0, v24
	v_max_f32_e32 v25, 0, v25
	v_max_f32_e32 v26, 0, v26
	v_max_f32_e32 v27, 0, v27
	v_mul_f32_e32 v28, v28, v28
	v_mul_f32_e32 v29, v29, v29
	v_mul_f32_e32 v30, v30, v30
	v_mul_f32_e32 v31, v31, v31
	v_mul_f32_e32 v24, v24, v24
	v_mul_f32_e32 v25, v25, v25
	v_mul_f32_e32 v26, v26, v26
	v_mul_f32_e32 v27, v27, v27
	v_cvt_pk_f16_f32 v28, v28, v29
	v_cvt_pk_f16_f32 v29, v30, v31
	v_cvt_pk_f16_f32 v30, v24, v25
	v_cvt_pk_f16_f32 v31, v26, v27
	s_nop 1
	v_permlane16_swap_b32_e32 v28, v30
	v_permlane16_swap_b32_e32 v29, v31
	v_mul_f32_e32 v20, v129, v20
	v_mul_f32_e32 v21, v129, v21
	v_mul_f32_e32 v22, v129, v22
	v_mul_f32_e32 v23, v129, v23
	v_mul_f32_e32 v16, v129, v16
	v_mul_f32_e32 v17, v129, v17
	v_mul_f32_e32 v18, v129, v18
	v_mul_f32_e32 v19, v129, v19
	v_max_f32_e32 v20, 0, v20
	v_max_f32_e32 v21, 0, v21
	v_max_f32_e32 v22, 0, v22
	v_max_f32_e32 v23, 0, v23
	v_max_f32_e32 v16, 0, v16
	v_max_f32_e32 v17, 0, v17
	v_max_f32_e32 v18, 0, v18
	v_max_f32_e32 v19, 0, v19
	v_mul_f32_e32 v20, v20, v20
	v_mul_f32_e32 v21, v21, v21
	v_mul_f32_e32 v22, v22, v22
	v_mul_f32_e32 v23, v23, v23
	v_mul_f32_e32 v16, v16, v16
	v_mul_f32_e32 v17, v17, v17
	v_mul_f32_e32 v18, v18, v18
; DI unsigned pack2(float lo, float hi) { f2_t v = {lo, hi}; h2_t b = __builtin_convertvector(v, h2_t); return __builtin_bit_cast(unsigned, b); }
; template <int VAR> DI void phase_up(const Params& P, int l, char* smem) {
;     ...
; #pragma unroll
;     for (int mt = 0; mt < 4; ++mt) {
;       const int row = row0 + mt * 16 + lr;
; #pragma unroll
;       for (int nt = 0; nt < 4; ++nt) {
;         float v[4];
; #pragma unroll
;         for (int j = 0; j < 4; ++j) { const float a = fmaxf(acc[mt][nt][j] * rs[mt], 0.f); v[j] = a * a; }
;         *(uint2*)(U + (size_t)row * DFF + col0 + nt * 16 + 4 * g) = make_uint2(pack2(v[0], v[1]), pack2(v[2], v[3]));
;       }
	v_mul_f32_e32 v19, v19, v19
	v_cvt_pk_f16_f32 v20, v20, v21
	v_cvt_pk_f16_f32 v21, v22, v23
	v_cvt_pk_f16_f32 v22, v16, v17
	v_cvt_pk_f16_f32 v23, v18, v19
	s_nop 1
	v_permlane16_swap_b32_e32 v20, v22
	v_permlane16_swap_b32_e32 v21, v23
	s_nop 1
	v_mov_b32_dpp v240, v28 row_ror:8 row_mask:0xf bank_mask:0x3
	v_mov_b32_dpp v241, v29 row_ror:8 row_mask:0xf bank_mask:0x3
	v_mov_b32_dpp v242, v30 row_ror:8 row_mask:0xf bank_mask:0x3
	v_mov_b32_dpp v243, v31 row_ror:8 row_mask:0xf bank_mask:0x3
	v_mov_b32_dpp v28, v20 row_ror:8 row_mask:0xf bank_mask:0xc
	v_mov_b32_dpp v29, v21 row_ror:8 row_mask:0xf bank_mask:0xc
	v_mov_b32_dpp v30, v22 row_ror:8 row_mask:0xf bank_mask:0xc
	v_mov_b32_dpp v31, v23 row_ror:8 row_mask:0xf bank_mask:0xc
	v_mov_b32_dpp v20, v240 quad_perm:[0,1,2,3] row_mask:0xf bank_mask:0x3
	v_mov_b32_dpp v21, v241 quad_perm:[0,1,2,3] row_mask:0xf bank_mask:0x3
	v_mov_b32_dpp v22, v242 quad_perm:[0,1,2,3] row_mask:0xf bank_mask:0x3
	v_mov_b32_dpp v23, v243 quad_perm:[0,1,2,3] row_mask:0xf bank_mask:0x3
	global_store_dwordx4 v[46:47], v[28:31], off
	global_store_dwordx4 v[48:49], v[20:23], off
	v_lshlrev_b64 v[46:47], 13, v[104:105]
	v_lshl_add_u64 v[46:47], v[44:45], 0, v[46:47]
	v_lshl_add_u64 v[48:49], v[248:249], 0, v[46:47]
	v_mul_f32_e32 v12, v127, v12
	v_mul_f32_e32 v13, v127, v13
	v_mul_f32_e32 v14, v127, v14
	v_mul_f32_e32 v15, v127, v15
	v_mul_f32_e32 v8, v127, v8
	v_mul_f32_e32 v9, v127, v9
	v_mul_f32_e32 v10, v127, v10
	v_mul_f32_e32 v11, v127, v11
	v_max_f32_e32 v12, 0, v12
	v_max_f32_e32 v13, 0, v13
	v_max_f32_e32 v14, 0, v14
	v_max_f32_e32 v15, 0, v15
	v_max_f32_e32 v8, 0, v8
	v_max_f32_e32 v9, 0, v9
	v_max_f32_e32 v10, 0, v10
	v_max_f32_e32 v11, 0, v11
	v_mul_f32_e32 v12, v12, v12
	v_mul_f32_e32 v13, v13, v13
	v_mul_f32_e32 v14, v14, v14
	v_mul_f32_e32 v15, v15, v15
	v_mul_f32_e32 v8, v8, v8
	v_mul_f32_e32 v9, v9, v9
	v_mul_f32_e32 v10, v10, v10
	v_mul_f32_e32 v11, v11, v11
	v_cvt_pk_f16_f32 v12, v12, v13
	v_cvt_pk_f16_f32 v13, v14, v15
	v_cvt_pk_f16_f32 v14, v8, v9
	v_cvt_pk_f16_f32 v15, v10, v11
	s_nop 1
	v_permlane16_swap_b32_e32 v12, v14
	v_permlane16_swap_b32_e32 v13, v15
	v_mul_f32_e32 v4, v127, v4
	v_mul_f32_e32 v5, v127, v5
	v_mul_f32_e32 v6, v127, v6
	v_mul_f32_e32 v7, v127, v7
	v_mul_f32_e32 v0, v127, v0
	v_mul_f32_e32 v1, v127, v1
	v_mul_f32_e32 v2, v127, v2
	v_mul_f32_e32 v3, v127, v3
	v_max_f32_e32 v4, 0, v4
	v_max_f32_e32 v5, 0, v5
	v_max_f32_e32 v6, 0, v6
	v_max_f32_e32 v7, 0, v7
	v_max_f32_e32 v0, 0, v0
	v_max_f32_e32 v1, 0, v1
	v_max_f32_e32 v2, 0, v2
	v_max_f32_e32 v3, 0, v3
	v_mul_f32_e32 v4, v4, v4
	v_mul_f32_e32 v5, v5, v5
	v_mul_f32_e32 v6, v6, v6
	v_mul_f32_e32 v7, v7, v7
	v_mul_f32_e32 v0, v0, v0
	v_mul_f32_e32 v1, v1, v1
	v_mul_f32_e32 v2, v2, v2
	v_mul_f32_e32 v3, v3, v3
	v_cvt_pk_f16_f32 v4, v4, v5
	v_cvt_pk_f16_f32 v5, v6, v7
	v_cvt_pk_f16_f32 v6, v0, v1
	v_cvt_pk_f16_f32 v7, v2, v3
	s_nop 1
	v_permlane16_swap_b32_e32 v4, v6
	v_permlane16_swap_b32_e32 v5, v7
	s_nop 1
	v_mov_b32_dpp v240, v12 row_ror:8 row_mask:0xf bank_mask:0x3
	v_mov_b32_dpp v241, v13 row_ror:8 row_mask:0xf bank_mask:0x3
	v_mov_b32_dpp v242, v14 row_ror:8 row_mask:0xf bank_mask:0x3
	v_mov_b32_dpp v243, v15 row_ror:8 row_mask:0xf bank_mask:0x3
	v_mov_b32_dpp v12, v4 row_ror:8 row_mask:0xf bank_mask:0xc
	v_mov_b32_dpp v13, v5 row_ror:8 row_mask:0xf bank_mask:0xc
	v_mov_b32_dpp v14, v6 row_ror:8 row_mask:0xf bank_mask:0xc
	v_mov_b32_dpp v15, v7 row_ror:8 row_mask:0xf bank_mask:0xc
	v_mov_b32_dpp v4, v240 quad_perm:[0,1,2,3] row_mask:0xf bank_mask:0x3
	v_mov_b32_dpp v5, v241 quad_perm:[0,1,2,3] row_mask:0xf bank_mask:0x3
	v_mov_b32_dpp v6, v242 quad_perm:[0,1,2,3] row_mask:0xf bank_mask:0x3
	v_mov_b32_dpp v7, v243 quad_perm:[0,1,2,3] row_mask:0xf bank_mask:0x3
	global_store_dwordx4 v[46:47], v[12:15], off
	global_store_dwordx4 v[48:49], v[4:7], off
	s_branch .LBB0_1312
